# all five GEMM K-loops: SGPR-base LDS-DMA addressing + counted lgkmcnt ladder in MFMA sections
# speedup vs baseline: 1.0174x; 1.0094x over previous
.LBB0_727:
	s_add_i32 s14, s14, 2
	s_add_u32 s40, s30, s12
	s_addc_u32 s41, s31, s13
	s_add_u32 s84, s26, s12
	s_addc_u32 s85, s27, s13
	s_add_i32 s86, 0, 0x10000
	v_add_u32_e32 v161, s86, v149
	ds_read_b128 v[134:137], v161
	ds_read_b128 v[152:155], v161 offset:1024
	ds_read_b128 v[162:165], v161 offset:2048
	ds_read_b128 v[166:169], v161 offset:3072
	s_cmp_eq_u32 s12, s22
	s_cselect_b32 s61, s51, s41
	s_cselect_b32 s60, s50, s40
	s_cselect_b32 s41, s49, s85
	s_cselect_b32 s40, s80, s84
	v_lshl_add_u64 v[202:203], v[132:133], 0, s[12:13]
	s_add_i32 m0, s66, 0xc000
	ds_read_b128 v[170:173], v160
	ds_read_b128 v[174:177], v160 offset:1024
	ds_read_b128 v[178:181], v160 offset:2048
	ds_read_b128 v[182:185], v160 offset:3072
	ds_read_b128 v[186:189], v160 offset:4096
	ds_read_b128 v[190:193], v160 offset:5120
	ds_read_b128 v[194:197], v160 offset:6144
	ds_read_b128 v[198:201], v160 offset:7168
	global_load_lds_dwordx4 v[202:203], off
	v_lshl_add_u64 v[202:203], v[130:131], 0, s[12:13]
	s_add_i32 m0, s66, 0xe000
	s_nop 0
	global_load_lds_dwordx4 v[202:203], off
	s_waitcnt lgkmcnt(8)
	s_barrier
	s_setprio 1
	s_waitcnt lgkmcnt(7)
	v_mfma_f32_16x16x32_bf16 v[126:129], v[134:137], v[170:173], v[126:129]
	v_mfma_f32_16x16x32_bf16 v[122:125], v[162:165], v[170:173], v[122:125]
	s_waitcnt lgkmcnt(5)
	v_mfma_f32_16x16x32_bf16 v[110:113], v[134:137], v[178:181], v[110:113]
	v_mfma_f32_16x16x32_bf16 v[106:109], v[162:165], v[178:181], v[106:109]
	s_waitcnt lgkmcnt(3)
	v_mfma_f32_16x16x32_bf16 v[94:97], v[134:137], v[186:189], v[94:97]
	v_mfma_f32_16x16x32_bf16 v[90:93], v[162:165], v[186:189], v[90:93]
	s_waitcnt lgkmcnt(1)
	v_mfma_f32_16x16x32_bf16 v[78:81], v[134:137], v[194:197], v[78:81]
	v_mfma_f32_16x16x32_bf16 v[74:77], v[162:165], v[194:197], v[74:77]
	v_mfma_f32_16x16x32_bf16 v[126:129], v[152:155], v[174:177], v[126:129]
	v_mfma_f32_16x16x32_bf16 v[122:125], v[166:169], v[174:177], v[122:125]
	v_mfma_f32_16x16x32_bf16 v[110:113], v[152:155], v[182:185], v[110:113]
	v_mfma_f32_16x16x32_bf16 v[106:109], v[166:169], v[182:185], v[106:109]
	v_mfma_f32_16x16x32_bf16 v[94:97], v[152:155], v[190:193], v[94:97]
	v_mfma_f32_16x16x32_bf16 v[90:93], v[166:169], v[190:193], v[90:93]
	s_waitcnt lgkmcnt(0)
	v_mfma_f32_16x16x32_bf16 v[78:81], v[152:155], v[198:201], v[78:81]
	v_mfma_f32_16x16x32_bf16 v[74:77], v[166:169], v[198:201], v[74:77]
	s_setprio 0
	s_barrier
	s_add_i32 s87, 0, 0x14000
	s_add_i32 s84, s86, s65
	v_add_u32_e32 v161, s87, v149
	s_mov_b32 m0, s84
	ds_read_b128 v[202:205], v161
	ds_read_b128 v[206:209], v161 offset:1024
	ds_read_b128 v[216:219], v161 offset:2048
	ds_read_b128 v[220:223], v161 offset:3072
	global_load_lds_dwordx4 v0, s[40:41]
	s_add_i32 m0, s84, 0x2000
	s_nop 0
	global_load_lds_dwordx4 v138, s[40:41]
	s_barrier
	s_setprio 1
	s_waitcnt lgkmcnt(3)
	v_mfma_f32_16x16x32_bf16 v[118:121], v[202:205], v[170:173], v[118:121]
	s_waitcnt lgkmcnt(1)
	v_mfma_f32_16x16x32_bf16 v[114:117], v[216:219], v[170:173], v[114:117]
	v_mfma_f32_16x16x32_bf16 v[102:105], v[202:205], v[178:181], v[102:105]
	v_mfma_f32_16x16x32_bf16 v[98:101], v[216:219], v[178:181], v[98:101]
	v_mfma_f32_16x16x32_bf16 v[86:89], v[202:205], v[186:189], v[86:89]
	v_mfma_f32_16x16x32_bf16 v[82:85], v[216:219], v[186:189], v[82:85]
	v_mfma_f32_16x16x32_bf16 v[70:73], v[202:205], v[194:197], v[70:73]
	v_mfma_f32_16x16x32_bf16 v[66:69], v[216:219], v[194:197], v[66:69]
	v_mfma_f32_16x16x32_bf16 v[118:121], v[206:209], v[174:177], v[118:121]
	s_waitcnt lgkmcnt(0)
	v_mfma_f32_16x16x32_bf16 v[114:117], v[220:223], v[174:177], v[114:117]
	v_mfma_f32_16x16x32_bf16 v[102:105], v[206:209], v[182:185], v[102:105]
	v_mfma_f32_16x16x32_bf16 v[98:101], v[220:223], v[182:185], v[98:101]
	v_mfma_f32_16x16x32_bf16 v[86:89], v[206:209], v[190:193], v[86:89]
	v_mfma_f32_16x16x32_bf16 v[82:85], v[220:223], v[190:193], v[82:85]
	v_mfma_f32_16x16x32_bf16 v[70:73], v[206:209], v[198:201], v[70:73]
	v_mfma_f32_16x16x32_bf16 v[66:69], v[220:223], v[198:201], v[66:69]
	s_setprio 0
	s_mov_b32 m0, s66
	s_add_u32 s98, s60, 0x80
	s_addc_u32 s99, s61, 0
	s_barrier
	ds_read_b128 v[170:173], v160 offset:16384
	ds_read_b128 v[174:177], v160 offset:17408
	ds_read_b128 v[178:181], v160 offset:18432
	ds_read_b128 v[182:185], v160 offset:19456
	ds_read_b128 v[186:189], v160 offset:20480
	ds_read_b128 v[190:193], v160 offset:21504
	ds_read_b128 v[194:197], v160 offset:22528
	ds_read_b128 v[198:201], v160 offset:23552
	global_load_lds_dwordx4 v142, s[60:61]
	s_mov_b32 m0, s67
	s_nop 0
	global_load_lds_dwordx4 v140, s[60:61]
	s_barrier
	s_setprio 1
	s_waitcnt lgkmcnt(7)
	v_mfma_f32_16x16x32_bf16 v[62:65], v[134:137], v[170:173], v[62:65]
	v_mfma_f32_16x16x32_bf16 v[58:61], v[162:165], v[170:173], v[58:61]
	s_waitcnt lgkmcnt(5)
	v_mfma_f32_16x16x32_bf16 v[46:49], v[134:137], v[178:181], v[46:49]
	v_mfma_f32_16x16x32_bf16 v[42:45], v[162:165], v[178:181], v[42:45]
	s_waitcnt lgkmcnt(3)
	v_mfma_f32_16x16x32_bf16 v[30:33], v[134:137], v[186:189], v[30:33]
	v_mfma_f32_16x16x32_bf16 v[26:29], v[162:165], v[186:189], v[26:29]
	s_waitcnt lgkmcnt(1)
	v_mfma_f32_16x16x32_bf16 v[14:17], v[134:137], v[194:197], v[14:17]
	v_mfma_f32_16x16x32_bf16 v[10:13], v[162:165], v[194:197], v[10:13]
	v_mfma_f32_16x16x32_bf16 v[62:65], v[152:155], v[174:177], v[62:65]
	v_mfma_f32_16x16x32_bf16 v[58:61], v[166:169], v[174:177], v[58:61]
	v_mfma_f32_16x16x32_bf16 v[46:49], v[152:155], v[182:185], v[46:49]
	v_mfma_f32_16x16x32_bf16 v[42:45], v[166:169], v[182:185], v[42:45]
	v_mfma_f32_16x16x32_bf16 v[30:33], v[152:155], v[190:193], v[30:33]
	v_mfma_f32_16x16x32_bf16 v[26:29], v[166:169], v[190:193], v[26:29]
	s_waitcnt lgkmcnt(0)
	v_mfma_f32_16x16x32_bf16 v[14:17], v[152:155], v[198:201], v[14:17]
	v_mfma_f32_16x16x32_bf16 v[10:13], v[166:169], v[198:201], v[10:13]
	s_setprio 0
	s_barrier
	s_add_u32 s84, s40, 0x100000
	s_addc_u32 s85, s41, 0
	s_add_i32 s86, s87, s65
	s_mov_b32 m0, s86
	s_nop 0
	global_load_lds_dwordx4 v0, s[84:85]
	s_add_i32 m0, s86, 0x2000
	s_nop 0
	global_load_lds_dwordx4 v138, s[84:85]
	s_waitcnt vmcnt(6)
	s_barrier
	s_setprio 1
	v_mfma_f32_16x16x32_bf16 v[54:57], v[202:205], v[170:173], v[54:57]
	v_mfma_f32_16x16x32_bf16 v[50:53], v[216:219], v[170:173], v[50:53]
	v_mfma_f32_16x16x32_bf16 v[38:41], v[202:205], v[178:181], v[38:41]
	v_mfma_f32_16x16x32_bf16 v[34:37], v[216:219], v[178:181], v[34:37]
	v_mfma_f32_16x16x32_bf16 v[22:25], v[202:205], v[186:189], v[22:25]
	v_mfma_f32_16x16x32_bf16 v[18:21], v[216:219], v[186:189], v[18:21]
	v_mfma_f32_16x16x32_bf16 v[6:9], v[202:205], v[194:197], v[6:9]
	v_mfma_f32_16x16x32_bf16 v[2:5], v[216:219], v[194:197], v[2:5]
	v_mfma_f32_16x16x32_bf16 v[54:57], v[206:209], v[174:177], v[54:57]
	v_mfma_f32_16x16x32_bf16 v[50:53], v[220:223], v[174:177], v[50:53]
	v_mfma_f32_16x16x32_bf16 v[38:41], v[206:209], v[182:185], v[38:41]
	v_mfma_f32_16x16x32_bf16 v[34:37], v[220:223], v[182:185], v[34:37]
	v_mfma_f32_16x16x32_bf16 v[22:25], v[206:209], v[190:193], v[22:25]
	v_mfma_f32_16x16x32_bf16 v[18:21], v[220:223], v[190:193], v[18:21]
	v_mfma_f32_16x16x32_bf16 v[6:9], v[206:209], v[198:201], v[6:9]
	v_mfma_f32_16x16x32_bf16 v[2:5], v[220:223], v[198:201], v[2:5]
	s_setprio 0
	s_add_i32 s84, 0, 0x18000
	v_add_u32_e32 v161, s84, v149
	s_barrier
	ds_read_b128 v[134:137], v161
	ds_read_b128 v[152:155], v161 offset:1024
	ds_read_b128 v[162:165], v161 offset:2048
	ds_read_b128 v[166:169], v161 offset:3072
	s_add_u32 s60, s60, 0x100000
	s_addc_u32 s61, s61, 0
	s_mov_b32 m0, s68
	ds_read_b128 v[170:173], v160 offset:32768
	ds_read_b128 v[174:177], v160 offset:33792
	ds_read_b128 v[178:181], v160 offset:34816
	ds_read_b128 v[182:185], v160 offset:35840
	ds_read_b128 v[186:189], v160 offset:36864
	ds_read_b128 v[190:193], v160 offset:37888
	ds_read_b128 v[194:197], v160 offset:38912
	ds_read_b128 v[198:201], v160 offset:39936
	global_load_lds_dwordx4 v142, s[60:61]
	s_mov_b32 m0, s69
	s_nop 0
	global_load_lds_dwordx4 v140, s[60:61]
	s_waitcnt lgkmcnt(8)
	s_barrier
	s_setprio 1
	s_waitcnt lgkmcnt(7)
	v_mfma_f32_16x16x32_bf16 v[126:129], v[134:137], v[170:173], v[126:129]
	v_mfma_f32_16x16x32_bf16 v[122:125], v[162:165], v[170:173], v[122:125]
	s_waitcnt lgkmcnt(5)
	v_mfma_f32_16x16x32_bf16 v[110:113], v[134:137], v[178:181], v[110:113]
	v_mfma_f32_16x16x32_bf16 v[106:109], v[162:165], v[178:181], v[106:109]
	s_waitcnt lgkmcnt(3)
	v_mfma_f32_16x16x32_bf16 v[94:97], v[134:137], v[186:189], v[94:97]
	v_mfma_f32_16x16x32_bf16 v[90:93], v[162:165], v[186:189], v[90:93]
	s_waitcnt lgkmcnt(1)
	v_mfma_f32_16x16x32_bf16 v[78:81], v[134:137], v[194:197], v[78:81]
	v_mfma_f32_16x16x32_bf16 v[74:77], v[162:165], v[194:197], v[74:77]
	v_mfma_f32_16x16x32_bf16 v[126:129], v[152:155], v[174:177], v[126:129]
	v_mfma_f32_16x16x32_bf16 v[122:125], v[166:169], v[174:177], v[122:125]
	v_mfma_f32_16x16x32_bf16 v[110:113], v[152:155], v[182:185], v[110:113]
	v_mfma_f32_16x16x32_bf16 v[106:109], v[166:169], v[182:185], v[106:109]
	v_mfma_f32_16x16x32_bf16 v[94:97], v[152:155], v[190:193], v[94:97]
	v_mfma_f32_16x16x32_bf16 v[90:93], v[166:169], v[190:193], v[90:93]
	s_waitcnt lgkmcnt(0)
	v_mfma_f32_16x16x32_bf16 v[78:81], v[152:155], v[198:201], v[78:81]
	v_mfma_f32_16x16x32_bf16 v[74:77], v[166:169], v[198:201], v[74:77]
	s_setprio 0
	s_barrier
	s_add_i32 s60, 0, 0x1c000
	s_add_i32 s61, s84, s65
	v_add_u32_e32 v161, s60, v149
	s_add_u32 s100, s40, 0x80
	s_addc_u32 s101, s41, 0
	s_mov_b32 m0, s61
	ds_read_b128 v[202:205], v161
	ds_read_b128 v[206:209], v161 offset:1024
	ds_read_b128 v[216:219], v161 offset:2048
	ds_read_b128 v[220:223], v161 offset:3072
	global_load_lds_dwordx4 v0, s[100:101]
	s_add_i32 m0, s61, 0x2000
	s_nop 0
	global_load_lds_dwordx4 v138, s[100:101]
	s_barrier
	s_setprio 1
	s_waitcnt lgkmcnt(3)
	v_mfma_f32_16x16x32_bf16 v[118:121], v[202:205], v[170:173], v[118:121]
	s_waitcnt lgkmcnt(1)
	v_mfma_f32_16x16x32_bf16 v[114:117], v[216:219], v[170:173], v[114:117]
	v_mfma_f32_16x16x32_bf16 v[102:105], v[202:205], v[178:181], v[102:105]
	v_mfma_f32_16x16x32_bf16 v[98:101], v[216:219], v[178:181], v[98:101]
	v_mfma_f32_16x16x32_bf16 v[86:89], v[202:205], v[186:189], v[86:89]
	v_mfma_f32_16x16x32_bf16 v[82:85], v[216:219], v[186:189], v[82:85]
	v_mfma_f32_16x16x32_bf16 v[70:73], v[202:205], v[194:197], v[70:73]
	v_mfma_f32_16x16x32_bf16 v[66:69], v[216:219], v[194:197], v[66:69]
	v_mfma_f32_16x16x32_bf16 v[118:121], v[206:209], v[174:177], v[118:121]
	s_waitcnt lgkmcnt(0)
	v_mfma_f32_16x16x32_bf16 v[114:117], v[220:223], v[174:177], v[114:117]
	v_mfma_f32_16x16x32_bf16 v[102:105], v[206:209], v[182:185], v[102:105]
	v_mfma_f32_16x16x32_bf16 v[98:101], v[220:223], v[182:185], v[98:101]
	v_mfma_f32_16x16x32_bf16 v[86:89], v[206:209], v[190:193], v[86:89]
	v_mfma_f32_16x16x32_bf16 v[82:85], v[220:223], v[190:193], v[82:85]
	v_mfma_f32_16x16x32_bf16 v[70:73], v[206:209], v[198:201], v[70:73]
	v_mfma_f32_16x16x32_bf16 v[66:69], v[220:223], v[198:201], v[66:69]
	s_setprio 0
	s_mov_b32 m0, s76
	s_barrier
	ds_read_b128 v[170:173], v160 offset:49152
	ds_read_b128 v[174:177], v160 offset:50176
	ds_read_b128 v[178:181], v160 offset:51200
	ds_read_b128 v[182:185], v160 offset:52224
	ds_read_b128 v[186:189], v160 offset:53248
	ds_read_b128 v[190:193], v160 offset:54272
	ds_read_b128 v[194:197], v160 offset:55296
	ds_read_b128 v[198:201], v160 offset:56320
	global_load_lds_dwordx4 v142, s[98:99]
	s_mov_b32 m0, s77
	s_nop 0
	global_load_lds_dwordx4 v140, s[98:99]
	s_barrier
	s_setprio 1
	s_waitcnt lgkmcnt(7)
	v_mfma_f32_16x16x32_bf16 v[62:65], v[134:137], v[170:173], v[62:65]
	v_mfma_f32_16x16x32_bf16 v[58:61], v[162:165], v[170:173], v[58:61]
	s_waitcnt lgkmcnt(5)
	v_mfma_f32_16x16x32_bf16 v[46:49], v[134:137], v[178:181], v[46:49]
	v_mfma_f32_16x16x32_bf16 v[42:45], v[162:165], v[178:181], v[42:45]
	s_waitcnt lgkmcnt(3)
	v_mfma_f32_16x16x32_bf16 v[30:33], v[134:137], v[186:189], v[30:33]
	v_mfma_f32_16x16x32_bf16 v[26:29], v[162:165], v[186:189], v[26:29]
	s_waitcnt lgkmcnt(1)
	v_mfma_f32_16x16x32_bf16 v[14:17], v[134:137], v[194:197], v[14:17]
	v_mfma_f32_16x16x32_bf16 v[10:13], v[162:165], v[194:197], v[10:13]
	v_mfma_f32_16x16x32_bf16 v[62:65], v[152:155], v[174:177], v[62:65]
	v_mfma_f32_16x16x32_bf16 v[58:61], v[166:169], v[174:177], v[58:61]
	v_mfma_f32_16x16x32_bf16 v[46:49], v[152:155], v[182:185], v[46:49]
	v_mfma_f32_16x16x32_bf16 v[42:45], v[166:169], v[182:185], v[42:45]
	v_mfma_f32_16x16x32_bf16 v[30:33], v[152:155], v[190:193], v[30:33]
	v_mfma_f32_16x16x32_bf16 v[26:29], v[166:169], v[190:193], v[26:29]
	s_waitcnt lgkmcnt(0)
	v_mfma_f32_16x16x32_bf16 v[14:17], v[152:155], v[198:201], v[14:17]
	v_mfma_f32_16x16x32_bf16 v[10:13], v[166:169], v[198:201], v[10:13]
	s_setprio 0
	s_barrier
	s_add_u32 s40, s40, 0x100080
	s_addc_u32 s41, s41, 0
	s_add_i32 s60, s60, s65
	s_mov_b32 m0, s60
	s_nop 0
	global_load_lds_dwordx4 v0, s[40:41]
	s_add_i32 m0, s60, 0x2000
	s_nop 0
	global_load_lds_dwordx4 v138, s[40:41]
	s_waitcnt vmcnt(6)
	s_barrier
	s_setprio 1
	v_mfma_f32_16x16x32_bf16 v[54:57], v[202:205], v[170:173], v[54:57]
	v_mfma_f32_16x16x32_bf16 v[50:53], v[216:219], v[170:173], v[50:53]
	v_mfma_f32_16x16x32_bf16 v[38:41], v[202:205], v[178:181], v[38:41]
	v_mfma_f32_16x16x32_bf16 v[34:37], v[216:219], v[178:181], v[34:37]
	v_mfma_f32_16x16x32_bf16 v[22:25], v[202:205], v[186:189], v[22:25]
	v_mfma_f32_16x16x32_bf16 v[18:21], v[216:219], v[186:189], v[18:21]
	v_mfma_f32_16x16x32_bf16 v[6:9], v[202:205], v[194:197], v[6:9]
	v_mfma_f32_16x16x32_bf16 v[2:5], v[216:219], v[194:197], v[2:5]
	v_mfma_f32_16x16x32_bf16 v[54:57], v[206:209], v[174:177], v[54:57]
	v_mfma_f32_16x16x32_bf16 v[50:53], v[220:223], v[174:177], v[50:53]
	v_mfma_f32_16x16x32_bf16 v[38:41], v[206:209], v[182:185], v[38:41]
	v_mfma_f32_16x16x32_bf16 v[34:37], v[220:223], v[182:185], v[34:37]
	v_mfma_f32_16x16x32_bf16 v[22:25], v[206:209], v[190:193], v[22:25]
	v_mfma_f32_16x16x32_bf16 v[18:21], v[220:223], v[190:193], v[18:21]
	v_mfma_f32_16x16x32_bf16 v[6:9], v[206:209], v[198:201], v[6:9]
	v_mfma_f32_16x16x32_bf16 v[2:5], v[220:223], v[198:201], v[2:5]
	s_setprio 0
	s_add_u32 s30, s30, 0x100
	s_addc_u32 s31, s31, 0
	s_add_u32 s26, s26, 0x100
	s_addc_u32 s27, s27, 0
	s_add_u32 s22, s22, 0xffffff00
	s_addc_u32 s23, s23, -1
	v_lshl_add_u64 v[132:133], v[132:133], 0, s[18:19]
	s_cmp_ge_u32 s14, vcc_lo
	v_lshl_add_u64 v[130:131], v[130:131], 0, s[18:19]
	s_barrier
	s_cbranch_scc0 .LBB0_727
	s_mov_b32 s14, 32
	s_mov_b64 s[26:27], 0
	s_andn2_b64 vcc, exec, s[6:7]
	s_mov_b64 s[6:7], -1
	s_cbranch_vccnz .LBB0_724
	v_mov_b32_e32 v130, v148
	v_mov_b64_e32 v[134:135], s[38:39]
	v_and_or_b32 v132, v130, 15, s82
	v_lshrrev_b32_e32 v130, 1, v130
	v_and_or_b32 v130, v130, 24, s75
	v_or_b32_e32 v130, s81, v130
	s_mov_b32 s14, s48
	v_ashrrev_i32_e32 v131, 31, v130
	v_mad_i64_i32 v[136:137], s[0:1], v132, s47, v[134:135]
	v_lshlrev_b64 v[130:131], 1, v[130:131]
	v_lshl_add_u64 v[136:137], v[136:137], 0, v[130:131]
	v_add_co_u32_e32 v152, vcc, s72, v136
	v_ashrrev_i32_e32 v133, 31, v132
	s_nop 0
	v_addc_co_u32_e32 v153, vcc, 0, v137, vcc
	global_load_dwordx4 v[152:155], v[152:153], off
	v_lshlrev_b64 v[156:157], 12, v[132:133]
	v_lshl_add_u64 v[156:157], s[28:29], 0, v[156:157]
	v_lshl_add_u64 v[156:157], v[156:157], 0, v[130:131]
	v_lshl_add_u64 v[136:137], v[136:137], 0, s[34:35]
	s_mov_b32 s22, s79
	s_mov_b64 s[6:7], s[52:53]
	s_mov_b64 s[12:13], s[50:51]
	s_waitcnt vmcnt(0)
	v_lshlrev_b32_e32 v158, 16, v152
	v_and_b32_e32 v159, 0xffff0000, v152
	v_lshlrev_b32_e32 v152, 16, v153
	v_and_b32_e32 v153, 0xffff0000, v153
	v_lshlrev_b32_e32 v162, 16, v154
	v_and_b32_e32 v163, 0xffff0000, v154
	v_lshlrev_b32_e32 v154, 16, v155
	v_and_b32_e32 v155, 0xffff0000, v155
	v_pk_mul_f32 v[128:129], v[128:129], v[152:153]
	v_pk_mul_f32 v[126:127], v[126:127], v[158:159]
	v_pk_mul_f32 v[152:153], v[124:125], v[154:155]
	v_pk_mul_f32 v[124:125], v[122:123], v[162:163]
	v_cvt_pk_bf16_f32 v122, v126, v127
	v_cvt_pk_bf16_f32 v123, v128, v129
	v_cvt_pk_bf16_f32 v124, v124, v125
	v_cvt_pk_bf16_f32 v125, v152, v153
	global_store_dwordx4 v[156:157], v[122:125], off
	global_load_dwordx4 v[122:125], v[136:137], off offset:256
	v_add_u32_e32 v126, 16, v132
	v_mad_i64_i32 v[128:129], s[0:1], v126, s47, v[134:135]
	v_lshl_add_u64 v[128:129], v[128:129], 0, v[130:131]
	v_add_co_u32_e32 v136, vcc, s72, v128
	v_ashrrev_i32_e32 v127, 31, v126
	s_nop 0
	v_addc_co_u32_e32 v137, vcc, 0, v129, vcc
	s_waitcnt vmcnt(0)
	v_lshlrev_b32_e32 v152, 16, v122
	v_and_b32_e32 v153, 0xffff0000, v122
	v_lshlrev_b32_e32 v122, 16, v123
	v_and_b32_e32 v123, 0xffff0000, v123
	v_lshlrev_b32_e32 v154, 16, v124
	v_and_b32_e32 v155, 0xffff0000, v124
	v_lshlrev_b32_e32 v124, 16, v125
	v_and_b32_e32 v125, 0xffff0000, v125
	v_pk_mul_f32 v[120:121], v[120:121], v[122:123]
	v_pk_mul_f32 v[118:119], v[118:119], v[152:153]
	v_pk_mul_f32 v[122:123], v[116:117], v[124:125]
	v_pk_mul_f32 v[116:117], v[114:115], v[154:155]
	v_cvt_pk_bf16_f32 v114, v118, v119
	v_cvt_pk_bf16_f32 v115, v120, v121
	v_cvt_pk_bf16_f32 v116, v116, v117
	v_cvt_pk_bf16_f32 v117, v122, v123
	global_store_dwordx4 v[156:157], v[114:117], off offset:256
	global_load_dwordx4 v[114:117], v[136:137], off
	v_lshlrev_b64 v[118:119], 12, v[126:127]
	v_lshl_add_u64 v[118:119], s[28:29], 0, v[118:119]
	v_lshl_add_u64 v[118:119], v[118:119], 0, v[130:131]
	v_lshl_add_u64 v[120:121], v[128:129], 0, s[34:35]
	s_waitcnt vmcnt(0)
	v_lshlrev_b32_e32 v122, 16, v114
	v_and_b32_e32 v123, 0xffff0000, v114
	v_lshlrev_b32_e32 v114, 16, v115
	v_and_b32_e32 v115, 0xffff0000, v115
	v_lshlrev_b32_e32 v124, 16, v116
	v_and_b32_e32 v125, 0xffff0000, v116
	v_lshlrev_b32_e32 v116, 16, v117
	v_and_b32_e32 v117, 0xffff0000, v117
	v_pk_mul_f32 v[112:113], v[112:113], v[114:115]
	v_pk_mul_f32 v[110:111], v[110:111], v[122:123]
	v_pk_mul_f32 v[114:115], v[108:109], v[116:117]
	v_pk_mul_f32 v[108:109], v[106:107], v[124:125]
	v_cvt_pk_bf16_f32 v106, v110, v111
	v_cvt_pk_bf16_f32 v107, v112, v113
	v_cvt_pk_bf16_f32 v108, v108, v109
	v_cvt_pk_bf16_f32 v109, v114, v115
	global_store_dwordx4 v[118:119], v[106:109], off
	global_load_dwordx4 v[106:109], v[120:121], off offset:256
	v_add_u32_e32 v110, 32, v132
	v_mad_i64_i32 v[112:113], s[0:1], v110, s47, v[134:135]
	v_lshl_add_u64 v[112:113], v[112:113], 0, v[130:131]
	v_add_co_u32_e32 v114, vcc, s72, v112
	v_ashrrev_i32_e32 v111, 31, v110
	s_nop 0
	v_addc_co_u32_e32 v115, vcc, 0, v113, vcc
	s_waitcnt vmcnt(0)
	v_lshlrev_b32_e32 v116, 16, v106
	v_and_b32_e32 v117, 0xffff0000, v106
	v_lshlrev_b32_e32 v106, 16, v107
	v_and_b32_e32 v107, 0xffff0000, v107
	v_lshlrev_b32_e32 v120, 16, v108
	v_and_b32_e32 v121, 0xffff0000, v108
	v_lshlrev_b32_e32 v108, 16, v109
	v_and_b32_e32 v109, 0xffff0000, v109
	v_pk_mul_f32 v[104:105], v[104:105], v[106:107]
	v_pk_mul_f32 v[102:103], v[102:103], v[116:117]
	v_pk_mul_f32 v[106:107], v[100:101], v[108:109]
	v_pk_mul_f32 v[100:101], v[98:99], v[120:121]
	v_cvt_pk_bf16_f32 v98, v102, v103
	v_cvt_pk_bf16_f32 v99, v104, v105
	v_cvt_pk_bf16_f32 v100, v100, v101
	v_cvt_pk_bf16_f32 v101, v106, v107
	global_store_dwordx4 v[118:119], v[98:101], off offset:256
	global_load_dwordx4 v[98:101], v[114:115], off
	v_lshlrev_b64 v[102:103], 12, v[110:111]
	v_lshl_add_u64 v[102:103], s[28:29], 0, v[102:103]
	v_lshl_add_u64 v[102:103], v[102:103], 0, v[130:131]
	v_lshl_add_u64 v[104:105], v[112:113], 0, s[34:35]
	s_waitcnt vmcnt(0)
	v_lshlrev_b32_e32 v106, 16, v98
	v_and_b32_e32 v107, 0xffff0000, v98
	v_lshlrev_b32_e32 v98, 16, v99
	v_and_b32_e32 v99, 0xffff0000, v99
	v_lshlrev_b32_e32 v108, 16, v100
	v_and_b32_e32 v109, 0xffff0000, v100
	v_lshlrev_b32_e32 v100, 16, v101
	v_and_b32_e32 v101, 0xffff0000, v101
	v_pk_mul_f32 v[96:97], v[96:97], v[98:99]
	v_pk_mul_f32 v[94:95], v[94:95], v[106:107]
	v_pk_mul_f32 v[98:99], v[92:93], v[100:101]
	v_pk_mul_f32 v[92:93], v[90:91], v[108:109]
	v_cvt_pk_bf16_f32 v90, v94, v95
	v_cvt_pk_bf16_f32 v91, v96, v97
	v_cvt_pk_bf16_f32 v92, v92, v93
	v_cvt_pk_bf16_f32 v93, v98, v99
	global_store_dwordx4 v[102:103], v[90:93], off
	global_load_dwordx4 v[90:93], v[104:105], off offset:256
	v_add_u32_e32 v94, 48, v132
	v_mad_i64_i32 v[96:97], s[0:1], v94, s47, v[134:135]
	v_lshl_add_u64 v[96:97], v[96:97], 0, v[130:131]
	v_add_co_u32_e32 v98, vcc, s72, v96
	v_ashrrev_i32_e32 v95, 31, v94
	s_nop 0
	v_addc_co_u32_e32 v99, vcc, 0, v97, vcc
	s_waitcnt vmcnt(0)
	v_lshlrev_b32_e32 v100, 16, v90
	v_and_b32_e32 v101, 0xffff0000, v90
	v_lshlrev_b32_e32 v90, 16, v91
	v_and_b32_e32 v91, 0xffff0000, v91
	v_lshlrev_b32_e32 v104, 16, v92
	v_and_b32_e32 v105, 0xffff0000, v92
	v_lshlrev_b32_e32 v92, 16, v93
	v_and_b32_e32 v93, 0xffff0000, v93
	v_pk_mul_f32 v[88:89], v[88:89], v[90:91]
	v_pk_mul_f32 v[86:87], v[86:87], v[100:101]
	v_pk_mul_f32 v[90:91], v[84:85], v[92:93]
	v_pk_mul_f32 v[84:85], v[82:83], v[104:105]
	v_cvt_pk_bf16_f32 v82, v86, v87
	v_cvt_pk_bf16_f32 v83, v88, v89
	v_cvt_pk_bf16_f32 v84, v84, v85
	v_cvt_pk_bf16_f32 v85, v90, v91
	global_store_dwordx4 v[102:103], v[82:85], off offset:256
	global_load_dwordx4 v[82:85], v[98:99], off
	v_lshlrev_b64 v[86:87], 12, v[94:95]
	v_lshl_add_u64 v[86:87], s[28:29], 0, v[86:87]
	v_lshl_add_u64 v[86:87], v[86:87], 0, v[130:131]
	v_lshl_add_u64 v[88:89], v[96:97], 0, s[34:35]
	s_waitcnt vmcnt(0)
	v_lshlrev_b32_e32 v90, 16, v82
	v_and_b32_e32 v91, 0xffff0000, v82
	v_lshlrev_b32_e32 v82, 16, v83
	v_and_b32_e32 v83, 0xffff0000, v83
	v_lshlrev_b32_e32 v92, 16, v84
	v_and_b32_e32 v93, 0xffff0000, v84
	v_lshlrev_b32_e32 v84, 16, v85
	v_and_b32_e32 v85, 0xffff0000, v85
	v_pk_mul_f32 v[80:81], v[80:81], v[82:83]
	v_pk_mul_f32 v[78:79], v[78:79], v[90:91]
	v_pk_mul_f32 v[82:83], v[76:77], v[84:85]
	v_pk_mul_f32 v[76:77], v[74:75], v[92:93]
	v_cvt_pk_bf16_f32 v74, v78, v79
	v_cvt_pk_bf16_f32 v75, v80, v81
	v_cvt_pk_bf16_f32 v76, v76, v77
	v_cvt_pk_bf16_f32 v77, v82, v83
	global_store_dwordx4 v[86:87], v[74:77], off
	global_load_dwordx4 v[74:77], v[88:89], off offset:256
	v_add_u32_e32 v78, 0x80, v132
	v_mad_i64_i32 v[80:81], s[0:1], v78, s47, v[134:135]
	v_lshl_add_u64 v[80:81], v[80:81], 0, v[130:131]
	v_add_co_u32_e32 v82, vcc, s72, v80
	v_ashrrev_i32_e32 v79, 31, v78
	s_nop 0
	v_addc_co_u32_e32 v83, vcc, 0, v81, vcc
	s_waitcnt vmcnt(0)
	v_lshlrev_b32_e32 v84, 16, v74
	v_and_b32_e32 v85, 0xffff0000, v74
	v_lshlrev_b32_e32 v74, 16, v75
	v_and_b32_e32 v75, 0xffff0000, v75
	v_lshlrev_b32_e32 v88, 16, v76
	v_and_b32_e32 v89, 0xffff0000, v76
	v_lshlrev_b32_e32 v76, 16, v77
	v_and_b32_e32 v77, 0xffff0000, v77
	v_pk_mul_f32 v[72:73], v[72:73], v[74:75]
	v_pk_mul_f32 v[70:71], v[70:71], v[84:85]
	v_pk_mul_f32 v[74:75], v[68:69], v[76:77]
	v_pk_mul_f32 v[68:69], v[66:67], v[88:89]
	v_cvt_pk_bf16_f32 v66, v70, v71
	v_cvt_pk_bf16_f32 v67, v72, v73
	v_cvt_pk_bf16_f32 v68, v68, v69
	v_cvt_pk_bf16_f32 v69, v74, v75
	global_store_dwordx4 v[86:87], v[66:69], off offset:256
	global_load_dwordx4 v[66:69], v[82:83], off
	v_lshlrev_b64 v[70:71], 12, v[78:79]
	v_lshl_add_u64 v[70:71], s[28:29], 0, v[70:71]
	v_lshl_add_u64 v[70:71], v[70:71], 0, v[130:131]
	v_lshl_add_u64 v[72:73], v[80:81], 0, s[34:35]
	s_waitcnt vmcnt(0)
	v_lshlrev_b32_e32 v74, 16, v66
	v_and_b32_e32 v75, 0xffff0000, v66
	v_lshlrev_b32_e32 v66, 16, v67
	v_and_b32_e32 v67, 0xffff0000, v67
	v_lshlrev_b32_e32 v76, 16, v68
	v_and_b32_e32 v77, 0xffff0000, v68
	v_lshlrev_b32_e32 v68, 16, v69
	v_and_b32_e32 v69, 0xffff0000, v69
	v_pk_mul_f32 v[64:65], v[64:65], v[66:67]
	v_pk_mul_f32 v[62:63], v[62:63], v[74:75]
	v_pk_mul_f32 v[66:67], v[60:61], v[68:69]
	v_pk_mul_f32 v[60:61], v[58:59], v[76:77]
	v_cvt_pk_bf16_f32 v58, v62, v63
	v_cvt_pk_bf16_f32 v59, v64, v65
	v_cvt_pk_bf16_f32 v60, v60, v61
	v_cvt_pk_bf16_f32 v61, v66, v67
	global_store_dwordx4 v[70:71], v[58:61], off
	global_load_dwordx4 v[58:61], v[72:73], off offset:256
	v_add_u32_e32 v62, 0x90, v132
	v_mad_i64_i32 v[64:65], s[0:1], v62, s47, v[134:135]
	v_lshl_add_u64 v[64:65], v[64:65], 0, v[130:131]
	v_add_co_u32_e32 v66, vcc, s72, v64
	v_ashrrev_i32_e32 v63, 31, v62
	s_nop 0
	v_addc_co_u32_e32 v67, vcc, 0, v65, vcc
	s_waitcnt vmcnt(0)
	v_lshlrev_b32_e32 v68, 16, v58
	v_and_b32_e32 v69, 0xffff0000, v58
	v_lshlrev_b32_e32 v58, 16, v59
	v_and_b32_e32 v59, 0xffff0000, v59
	v_lshlrev_b32_e32 v72, 16, v60
	v_and_b32_e32 v73, 0xffff0000, v60
	v_lshlrev_b32_e32 v60, 16, v61
	v_and_b32_e32 v61, 0xffff0000, v61
	v_pk_mul_f32 v[56:57], v[56:57], v[58:59]
	v_pk_mul_f32 v[54:55], v[54:55], v[68:69]
	v_pk_mul_f32 v[58:59], v[52:53], v[60:61]
	v_pk_mul_f32 v[52:53], v[50:51], v[72:73]
	v_cvt_pk_bf16_f32 v50, v54, v55
	v_cvt_pk_bf16_f32 v51, v56, v57
	v_cvt_pk_bf16_f32 v52, v52, v53
	v_cvt_pk_bf16_f32 v53, v58, v59
	global_store_dwordx4 v[70:71], v[50:53], off offset:256
	global_load_dwordx4 v[50:53], v[66:67], off
	v_lshlrev_b64 v[54:55], 12, v[62:63]
	v_lshl_add_u64 v[54:55], s[28:29], 0, v[54:55]
	v_lshl_add_u64 v[54:55], v[54:55], 0, v[130:131]
	v_lshl_add_u64 v[56:57], v[64:65], 0, s[34:35]
	s_waitcnt vmcnt(0)
	v_lshlrev_b32_e32 v58, 16, v50
	v_and_b32_e32 v59, 0xffff0000, v50
	v_lshlrev_b32_e32 v50, 16, v51
	v_and_b32_e32 v51, 0xffff0000, v51
	v_lshlrev_b32_e32 v60, 16, v52
	v_and_b32_e32 v61, 0xffff0000, v52
	v_lshlrev_b32_e32 v52, 16, v53
	v_and_b32_e32 v53, 0xffff0000, v53
	v_pk_mul_f32 v[48:49], v[48:49], v[50:51]
	v_pk_mul_f32 v[46:47], v[46:47], v[58:59]
	v_pk_mul_f32 v[50:51], v[44:45], v[52:53]
	v_pk_mul_f32 v[44:45], v[42:43], v[60:61]
	v_cvt_pk_bf16_f32 v42, v46, v47
	v_cvt_pk_bf16_f32 v43, v48, v49
	v_cvt_pk_bf16_f32 v44, v44, v45
	v_cvt_pk_bf16_f32 v45, v50, v51
	global_store_dwordx4 v[54:55], v[42:45], off
	global_load_dwordx4 v[42:45], v[56:57], off offset:256
	v_add_u32_e32 v46, 0xa0, v132
	v_mad_i64_i32 v[48:49], s[0:1], v46, s47, v[134:135]
	v_lshl_add_u64 v[48:49], v[48:49], 0, v[130:131]
	v_add_co_u32_e32 v50, vcc, s72, v48
	v_ashrrev_i32_e32 v47, 31, v46
	s_nop 0
	v_addc_co_u32_e32 v51, vcc, 0, v49, vcc
	s_waitcnt vmcnt(0)
	v_lshlrev_b32_e32 v52, 16, v42
	v_and_b32_e32 v53, 0xffff0000, v42
	v_lshlrev_b32_e32 v42, 16, v43
	v_and_b32_e32 v43, 0xffff0000, v43
	v_lshlrev_b32_e32 v56, 16, v44
	v_and_b32_e32 v57, 0xffff0000, v44
	v_lshlrev_b32_e32 v44, 16, v45
	v_and_b32_e32 v45, 0xffff0000, v45
	v_pk_mul_f32 v[40:41], v[40:41], v[42:43]
	v_pk_mul_f32 v[38:39], v[38:39], v[52:53]
	v_pk_mul_f32 v[42:43], v[36:37], v[44:45]
	v_pk_mul_f32 v[36:37], v[34:35], v[56:57]
	v_cvt_pk_bf16_f32 v34, v38, v39
	v_cvt_pk_bf16_f32 v35, v40, v41
	v_cvt_pk_bf16_f32 v36, v36, v37
	v_cvt_pk_bf16_f32 v37, v42, v43
	global_store_dwordx4 v[54:55], v[34:37], off offset:256
	global_load_dwordx4 v[34:37], v[50:51], off
	v_lshlrev_b64 v[38:39], 12, v[46:47]
	v_lshl_add_u64 v[38:39], s[28:29], 0, v[38:39]
	v_lshl_add_u64 v[38:39], v[38:39], 0, v[130:131]
	v_lshl_add_u64 v[40:41], v[48:49], 0, s[34:35]
	s_waitcnt vmcnt(0)
	v_lshlrev_b32_e32 v42, 16, v34
	v_and_b32_e32 v43, 0xffff0000, v34
	v_lshlrev_b32_e32 v34, 16, v35
	v_and_b32_e32 v35, 0xffff0000, v35
	v_lshlrev_b32_e32 v44, 16, v36
	v_and_b32_e32 v45, 0xffff0000, v36
	v_lshlrev_b32_e32 v36, 16, v37
	v_and_b32_e32 v37, 0xffff0000, v37
	v_pk_mul_f32 v[32:33], v[32:33], v[34:35]
	v_pk_mul_f32 v[30:31], v[30:31], v[42:43]
	v_pk_mul_f32 v[34:35], v[28:29], v[36:37]
	v_pk_mul_f32 v[28:29], v[26:27], v[44:45]
	v_cvt_pk_bf16_f32 v26, v30, v31
	v_cvt_pk_bf16_f32 v27, v32, v33
	v_cvt_pk_bf16_f32 v28, v28, v29
	v_cvt_pk_bf16_f32 v29, v34, v35
	global_store_dwordx4 v[38:39], v[26:29], off
	global_load_dwordx4 v[26:29], v[40:41], off offset:256
	v_add_u32_e32 v30, 0xb0, v132
	v_mad_i64_i32 v[32:33], s[0:1], v30, s47, v[134:135]
	v_lshl_add_u64 v[32:33], v[32:33], 0, v[130:131]
	v_add_co_u32_e32 v34, vcc, s72, v32
	v_ashrrev_i32_e32 v31, 31, v30
	s_nop 0
	v_addc_co_u32_e32 v35, vcc, 0, v33, vcc
	s_and_b64 vcc, exec, s[36:37]
	s_waitcnt vmcnt(0)
	v_lshlrev_b32_e32 v36, 16, v26
	v_and_b32_e32 v37, 0xffff0000, v26
	v_lshlrev_b32_e32 v26, 16, v27
	v_and_b32_e32 v27, 0xffff0000, v27
	v_lshlrev_b32_e32 v40, 16, v28
	v_and_b32_e32 v41, 0xffff0000, v28
	v_lshlrev_b32_e32 v28, 16, v29
	v_and_b32_e32 v29, 0xffff0000, v29
	v_pk_mul_f32 v[24:25], v[24:25], v[26:27]
	v_pk_mul_f32 v[22:23], v[22:23], v[36:37]
	v_pk_mul_f32 v[26:27], v[20:21], v[28:29]
	v_pk_mul_f32 v[20:21], v[18:19], v[40:41]
	v_cvt_pk_bf16_f32 v18, v22, v23
	v_cvt_pk_bf16_f32 v19, v24, v25
	v_cvt_pk_bf16_f32 v20, v20, v21
	v_cvt_pk_bf16_f32 v21, v26, v27
	global_store_dwordx4 v[38:39], v[18:21], off offset:256
	global_load_dwordx4 v[18:21], v[34:35], off
	v_lshlrev_b64 v[22:23], 12, v[30:31]
	v_lshl_add_u64 v[22:23], s[28:29], 0, v[22:23]
	v_lshl_add_u64 v[22:23], v[22:23], 0, v[130:131]
	v_lshl_add_u64 v[24:25], v[32:33], 0, s[34:35]
	s_waitcnt vmcnt(0)
	v_lshlrev_b32_e32 v26, 16, v18
	v_and_b32_e32 v27, 0xffff0000, v18
	v_lshlrev_b32_e32 v18, 16, v19
	v_and_b32_e32 v19, 0xffff0000, v19
	v_lshlrev_b32_e32 v28, 16, v20
	v_and_b32_e32 v29, 0xffff0000, v20
	v_lshlrev_b32_e32 v20, 16, v21
	v_and_b32_e32 v21, 0xffff0000, v21
	v_pk_mul_f32 v[16:17], v[16:17], v[18:19]
	v_pk_mul_f32 v[14:15], v[14:15], v[26:27]
	v_pk_mul_f32 v[18:19], v[12:13], v[20:21]
	v_pk_mul_f32 v[12:13], v[10:11], v[28:29]
	v_cvt_pk_bf16_f32 v10, v14, v15
	v_cvt_pk_bf16_f32 v11, v16, v17
	v_cvt_pk_bf16_f32 v12, v12, v13
	v_cvt_pk_bf16_f32 v13, v18, v19
	global_store_dwordx4 v[22:23], v[10:13], off
	global_load_dwordx4 v[10:13], v[24:25], off offset:256
	s_waitcnt vmcnt(0)
	v_lshlrev_b32_e32 v14, 16, v10
	v_and_b32_e32 v15, 0xffff0000, v10
	v_lshlrev_b32_e32 v10, 16, v11
	v_and_b32_e32 v11, 0xffff0000, v11
	v_lshlrev_b32_e32 v16, 16, v12
	v_and_b32_e32 v17, 0xffff0000, v12
	v_lshlrev_b32_e32 v12, 16, v13
	v_and_b32_e32 v13, 0xffff0000, v13
	v_pk_mul_f32 v[8:9], v[8:9], v[10:11]
	v_pk_mul_f32 v[6:7], v[6:7], v[14:15]
	v_pk_mul_f32 v[10:11], v[4:5], v[12:13]
	v_pk_mul_f32 v[4:5], v[2:3], v[16:17]
	v_cvt_pk_bf16_f32 v2, v6, v7
	v_cvt_pk_bf16_f32 v3, v8, v9
	v_cvt_pk_bf16_f32 v4, v4, v5
	v_cvt_pk_bf16_f32 v5, v10, v11
	global_store_dwordx4 v[22:23], v[2:5], off offset:256
	s_cbranch_vccz .LBB0_715
	s_waitcnt vmcnt(0)
	s_cmpk_gt_u32 s97, 0xff
	s_cbranch_scc1 .LBB0_732
	s_barrier

.LBB0_807:
	s_add_u32 s30, s6, s26
	s_addc_u32 s31, s7, s27
	s_add_u32 s30, s30, 0x100
	s_addc_u32 s31, s31, 0
	s_add_u32 s81, s79, s26
	s_addc_u32 s82, s80, s27
	s_add_i32 s83, 0, 0x10000
	v_add_u32_e32 v146, s83, v144
	ds_read_b128 v[152:155], v146
	ds_read_b128 v[156:159], v146 offset:1024
	ds_read_b128 v[160:163], v146 offset:2048
	ds_read_b128 v[164:167], v146 offset:3072
	s_cmpk_eq_i32 s26, 0xf00
	s_cselect_b32 s41, s23, s31
	s_cselect_b32 s40, s22, s30
	s_cselect_b32 s31, s9, s82
	s_cselect_b32 s30, s44, s81
	v_lshl_add_u64 v[146:147], v[140:141], 0, s[26:27]
	s_add_i32 m0, s61, 0xc000
	ds_read_b128 v[168:171], v145
	ds_read_b128 v[172:175], v145 offset:1024
	ds_read_b128 v[176:179], v145 offset:2048
	ds_read_b128 v[180:183], v145 offset:3072
	ds_read_b128 v[184:187], v145 offset:4096
	ds_read_b128 v[188:191], v145 offset:5120
	ds_read_b128 v[192:195], v145 offset:6144
	ds_read_b128 v[196:199], v145 offset:7168
	global_load_lds_dwordx4 v[146:147], off
	v_lshl_add_u64 v[146:147], v[142:143], 0, s[26:27]
	s_add_i32 m0, s61, 0xe000
	s_nop 0
	global_load_lds_dwordx4 v[146:147], off
	s_waitcnt lgkmcnt(8)
	s_barrier
	s_setprio 1
	s_waitcnt lgkmcnt(7)
	v_mfma_f32_16x16x32_bf16 v[126:129], v[152:155], v[168:171], v[126:129]
	v_mfma_f32_16x16x32_bf16 v[122:125], v[160:163], v[168:171], v[122:125]
	s_waitcnt lgkmcnt(5)
	v_mfma_f32_16x16x32_bf16 v[110:113], v[152:155], v[176:179], v[110:113]
	v_mfma_f32_16x16x32_bf16 v[106:109], v[160:163], v[176:179], v[106:109]
	s_waitcnt lgkmcnt(3)
	v_mfma_f32_16x16x32_bf16 v[94:97], v[152:155], v[184:187], v[94:97]
	v_mfma_f32_16x16x32_bf16 v[90:93], v[160:163], v[184:187], v[90:93]
	s_waitcnt lgkmcnt(1)
	v_mfma_f32_16x16x32_bf16 v[78:81], v[152:155], v[192:195], v[78:81]
	v_mfma_f32_16x16x32_bf16 v[74:77], v[160:163], v[192:195], v[74:77]
	v_mfma_f32_16x16x32_bf16 v[126:129], v[156:159], v[172:175], v[126:129]
	v_mfma_f32_16x16x32_bf16 v[122:125], v[164:167], v[172:175], v[122:125]
	v_mfma_f32_16x16x32_bf16 v[110:113], v[156:159], v[180:183], v[110:113]
	v_mfma_f32_16x16x32_bf16 v[106:109], v[164:167], v[180:183], v[106:109]
	v_mfma_f32_16x16x32_bf16 v[94:97], v[156:159], v[188:191], v[94:97]
	v_mfma_f32_16x16x32_bf16 v[90:93], v[164:167], v[188:191], v[90:93]
	s_waitcnt lgkmcnt(0)
	v_mfma_f32_16x16x32_bf16 v[78:81], v[156:159], v[196:199], v[78:81]
	v_mfma_f32_16x16x32_bf16 v[74:77], v[164:167], v[196:199], v[74:77]
	s_setprio 0
	s_barrier
	s_add_i32 s81, 0, 0x14000
	v_add_u32_e32 v146, s81, v144
	s_add_i32 s82, s83, s60
	ds_read_b128 v[200:203], v146
	ds_read_b128 v[204:207], v146 offset:1024
	ds_read_b128 v[216:219], v146 offset:2048
	ds_read_b128 v[220:223], v146 offset:3072
	s_mov_b32 m0, s82
	s_nop 0
	global_load_lds_dwordx4 v0, s[30:31]
	s_add_i32 m0, s82, 0x2000
	s_nop 0
	global_load_lds_dwordx4 v134, s[30:31]
	s_barrier
	s_setprio 1
	s_waitcnt lgkmcnt(3)
	v_mfma_f32_16x16x32_bf16 v[118:121], v[200:203], v[168:171], v[118:121]
	s_waitcnt lgkmcnt(1)
	v_mfma_f32_16x16x32_bf16 v[114:117], v[216:219], v[168:171], v[114:117]
	v_mfma_f32_16x16x32_bf16 v[102:105], v[200:203], v[176:179], v[102:105]
	v_mfma_f32_16x16x32_bf16 v[98:101], v[216:219], v[176:179], v[98:101]
	v_mfma_f32_16x16x32_bf16 v[86:89], v[200:203], v[184:187], v[86:89]
	v_mfma_f32_16x16x32_bf16 v[82:85], v[216:219], v[184:187], v[82:85]
	v_mfma_f32_16x16x32_bf16 v[70:73], v[200:203], v[192:195], v[70:73]
	v_mfma_f32_16x16x32_bf16 v[66:69], v[216:219], v[192:195], v[66:69]
	v_mfma_f32_16x16x32_bf16 v[118:121], v[204:207], v[172:175], v[118:121]
	s_waitcnt lgkmcnt(0)
	v_mfma_f32_16x16x32_bf16 v[114:117], v[220:223], v[172:175], v[114:117]
	v_mfma_f32_16x16x32_bf16 v[102:105], v[204:207], v[180:183], v[102:105]
	v_mfma_f32_16x16x32_bf16 v[98:101], v[220:223], v[180:183], v[98:101]
	v_mfma_f32_16x16x32_bf16 v[86:89], v[204:207], v[188:191], v[86:89]
	v_mfma_f32_16x16x32_bf16 v[82:85], v[220:223], v[188:191], v[82:85]
	v_mfma_f32_16x16x32_bf16 v[70:73], v[204:207], v[196:199], v[70:73]
	v_mfma_f32_16x16x32_bf16 v[66:69], v[220:223], v[196:199], v[66:69]
	s_setprio 0
	s_mov_b32 m0, s61
	s_add_u32 s98, s40, 0x80
	s_addc_u32 s99, s41, 0
	s_barrier
	ds_read_b128 v[168:171], v145 offset:16384
	ds_read_b128 v[172:175], v145 offset:17408
	ds_read_b128 v[176:179], v145 offset:18432
	ds_read_b128 v[180:183], v145 offset:19456
	ds_read_b128 v[184:187], v145 offset:20480
	ds_read_b128 v[188:191], v145 offset:21504
	ds_read_b128 v[192:195], v145 offset:22528
	ds_read_b128 v[196:199], v145 offset:23552
	global_load_lds_dwordx4 v0, s[40:41]
	s_mov_b32 m0, s64
	s_nop 0
	global_load_lds_dwordx4 v134, s[40:41]
	s_barrier
	s_setprio 1
	s_waitcnt lgkmcnt(7)
	v_mfma_f32_16x16x32_bf16 v[62:65], v[152:155], v[168:171], v[62:65]
	v_mfma_f32_16x16x32_bf16 v[58:61], v[160:163], v[168:171], v[58:61]
	s_waitcnt lgkmcnt(5)
	v_mfma_f32_16x16x32_bf16 v[46:49], v[152:155], v[176:179], v[46:49]
	v_mfma_f32_16x16x32_bf16 v[42:45], v[160:163], v[176:179], v[42:45]
	s_waitcnt lgkmcnt(3)
	v_mfma_f32_16x16x32_bf16 v[30:33], v[152:155], v[184:187], v[30:33]
	v_mfma_f32_16x16x32_bf16 v[26:29], v[160:163], v[184:187], v[26:29]
	s_waitcnt lgkmcnt(1)
	v_mfma_f32_16x16x32_bf16 v[14:17], v[152:155], v[192:195], v[14:17]
	v_mfma_f32_16x16x32_bf16 v[10:13], v[160:163], v[192:195], v[10:13]
	v_mfma_f32_16x16x32_bf16 v[62:65], v[156:159], v[172:175], v[62:65]
	v_mfma_f32_16x16x32_bf16 v[58:61], v[164:167], v[172:175], v[58:61]
	v_mfma_f32_16x16x32_bf16 v[46:49], v[156:159], v[180:183], v[46:49]
	v_mfma_f32_16x16x32_bf16 v[42:45], v[164:167], v[180:183], v[42:45]
	v_mfma_f32_16x16x32_bf16 v[30:33], v[156:159], v[188:191], v[30:33]
	v_mfma_f32_16x16x32_bf16 v[26:29], v[164:167], v[188:191], v[26:29]
	s_waitcnt lgkmcnt(0)
	v_mfma_f32_16x16x32_bf16 v[14:17], v[156:159], v[196:199], v[14:17]
	v_mfma_f32_16x16x32_bf16 v[10:13], v[164:167], v[196:199], v[10:13]
	s_setprio 0
	s_barrier
	s_add_u32 s82, s30, 0x80000
	s_addc_u32 s83, s31, 0
	s_add_i32 s81, s81, s60
	s_mov_b32 m0, s81
	s_nop 0
	global_load_lds_dwordx4 v0, s[82:83]
	s_add_i32 m0, s81, 0x2000
	s_nop 0
	global_load_lds_dwordx4 v134, s[82:83]
	s_waitcnt vmcnt(6)
	s_barrier
	s_setprio 1
	v_mfma_f32_16x16x32_bf16 v[54:57], v[200:203], v[168:171], v[54:57]
	v_mfma_f32_16x16x32_bf16 v[50:53], v[216:219], v[168:171], v[50:53]
	v_mfma_f32_16x16x32_bf16 v[38:41], v[200:203], v[176:179], v[38:41]
	v_mfma_f32_16x16x32_bf16 v[34:37], v[216:219], v[176:179], v[34:37]
	v_mfma_f32_16x16x32_bf16 v[22:25], v[200:203], v[184:187], v[22:25]
	v_mfma_f32_16x16x32_bf16 v[18:21], v[216:219], v[184:187], v[18:21]
	v_mfma_f32_16x16x32_bf16 v[6:9], v[200:203], v[192:195], v[6:9]
	v_mfma_f32_16x16x32_bf16 v[2:5], v[216:219], v[192:195], v[2:5]
	v_mfma_f32_16x16x32_bf16 v[54:57], v[204:207], v[172:175], v[54:57]
	v_mfma_f32_16x16x32_bf16 v[50:53], v[220:223], v[172:175], v[50:53]
	v_mfma_f32_16x16x32_bf16 v[38:41], v[204:207], v[180:183], v[38:41]
	v_mfma_f32_16x16x32_bf16 v[34:37], v[220:223], v[180:183], v[34:37]
	v_mfma_f32_16x16x32_bf16 v[22:25], v[204:207], v[188:191], v[22:25]
	v_mfma_f32_16x16x32_bf16 v[18:21], v[220:223], v[188:191], v[18:21]
	v_mfma_f32_16x16x32_bf16 v[6:9], v[204:207], v[196:199], v[6:9]
	v_mfma_f32_16x16x32_bf16 v[2:5], v[220:223], v[196:199], v[2:5]
	s_setprio 0
	s_add_i32 s81, 0, 0x18000
	v_add_u32_e32 v149, s81, v144
	s_barrier
	ds_read_b128 v[152:155], v149
	ds_read_b128 v[156:159], v149 offset:1024
	ds_read_b128 v[160:163], v149 offset:2048
	ds_read_b128 v[164:167], v149 offset:3072
	s_add_u32 s40, s40, 0x80000
	s_addc_u32 s41, s41, 0
	s_mov_b32 m0, s67
	ds_read_b128 v[168:171], v145 offset:32768
	ds_read_b128 v[172:175], v145 offset:33792
	ds_read_b128 v[176:179], v145 offset:34816
	ds_read_b128 v[180:183], v145 offset:35840
	ds_read_b128 v[184:187], v145 offset:36864
	ds_read_b128 v[188:191], v145 offset:37888
	ds_read_b128 v[192:195], v145 offset:38912
	ds_read_b128 v[196:199], v145 offset:39936
	global_load_lds_dwordx4 v0, s[40:41]
	s_mov_b32 m0, s68
	s_nop 0
	global_load_lds_dwordx4 v134, s[40:41]
	s_waitcnt lgkmcnt(8)
	s_barrier
	s_setprio 1
	s_waitcnt lgkmcnt(7)
	v_mfma_f32_16x16x32_bf16 v[126:129], v[152:155], v[168:171], v[126:129]
	v_mfma_f32_16x16x32_bf16 v[122:125], v[160:163], v[168:171], v[122:125]
	s_waitcnt lgkmcnt(5)
	v_mfma_f32_16x16x32_bf16 v[110:113], v[152:155], v[176:179], v[110:113]
	v_mfma_f32_16x16x32_bf16 v[106:109], v[160:163], v[176:179], v[106:109]
	s_waitcnt lgkmcnt(3)
	v_mfma_f32_16x16x32_bf16 v[94:97], v[152:155], v[184:187], v[94:97]
	v_mfma_f32_16x16x32_bf16 v[90:93], v[160:163], v[184:187], v[90:93]
	s_waitcnt lgkmcnt(1)
	v_mfma_f32_16x16x32_bf16 v[78:81], v[152:155], v[192:195], v[78:81]
	v_mfma_f32_16x16x32_bf16 v[74:77], v[160:163], v[192:195], v[74:77]
	v_mfma_f32_16x16x32_bf16 v[126:129], v[156:159], v[172:175], v[126:129]
	v_mfma_f32_16x16x32_bf16 v[122:125], v[164:167], v[172:175], v[122:125]
	v_mfma_f32_16x16x32_bf16 v[110:113], v[156:159], v[180:183], v[110:113]
	v_mfma_f32_16x16x32_bf16 v[106:109], v[164:167], v[180:183], v[106:109]
	v_mfma_f32_16x16x32_bf16 v[94:97], v[156:159], v[188:191], v[94:97]
	v_mfma_f32_16x16x32_bf16 v[90:93], v[164:167], v[188:191], v[90:93]
	s_waitcnt lgkmcnt(0)
	v_mfma_f32_16x16x32_bf16 v[78:81], v[156:159], v[196:199], v[78:81]
	v_mfma_f32_16x16x32_bf16 v[74:77], v[164:167], v[196:199], v[74:77]
	s_setprio 0
	s_barrier
	s_add_i32 s40, 0, 0x1c000
	s_add_i32 s41, s81, s60
	v_add_u32_e32 v149, s40, v144
	s_add_u32 s100, s30, 0x80
	s_addc_u32 s101, s31, 0
	s_mov_b32 m0, s41
	ds_read_b128 v[200:203], v149
	ds_read_b128 v[204:207], v149 offset:1024
	ds_read_b128 v[216:219], v149 offset:2048
	ds_read_b128 v[220:223], v149 offset:3072
	global_load_lds_dwordx4 v0, s[100:101]
	s_add_i32 m0, s41, 0x2000
	s_nop 0
	global_load_lds_dwordx4 v134, s[100:101]
	s_barrier
	s_setprio 1
	s_waitcnt lgkmcnt(3)
	v_mfma_f32_16x16x32_bf16 v[118:121], v[200:203], v[168:171], v[118:121]
	s_waitcnt lgkmcnt(1)
	v_mfma_f32_16x16x32_bf16 v[114:117], v[216:219], v[168:171], v[114:117]
	v_mfma_f32_16x16x32_bf16 v[102:105], v[200:203], v[176:179], v[102:105]
	v_mfma_f32_16x16x32_bf16 v[98:101], v[216:219], v[176:179], v[98:101]
	v_mfma_f32_16x16x32_bf16 v[86:89], v[200:203], v[184:187], v[86:89]
	v_mfma_f32_16x16x32_bf16 v[82:85], v[216:219], v[184:187], v[82:85]
	v_mfma_f32_16x16x32_bf16 v[70:73], v[200:203], v[192:195], v[70:73]
	v_mfma_f32_16x16x32_bf16 v[66:69], v[216:219], v[192:195], v[66:69]
	v_mfma_f32_16x16x32_bf16 v[118:121], v[204:207], v[172:175], v[118:121]
	s_waitcnt lgkmcnt(0)
	v_mfma_f32_16x16x32_bf16 v[114:117], v[220:223], v[172:175], v[114:117]
	v_mfma_f32_16x16x32_bf16 v[102:105], v[204:207], v[180:183], v[102:105]
	v_mfma_f32_16x16x32_bf16 v[98:101], v[220:223], v[180:183], v[98:101]
	v_mfma_f32_16x16x32_bf16 v[86:89], v[204:207], v[188:191], v[86:89]
	v_mfma_f32_16x16x32_bf16 v[82:85], v[220:223], v[188:191], v[82:85]
	v_mfma_f32_16x16x32_bf16 v[70:73], v[204:207], v[196:199], v[70:73]
	v_mfma_f32_16x16x32_bf16 v[66:69], v[220:223], v[196:199], v[66:69]
	s_setprio 0
	s_mov_b32 m0, s69
	s_barrier
	ds_read_b128 v[168:171], v145 offset:49152
	ds_read_b128 v[172:175], v145 offset:50176
	ds_read_b128 v[176:179], v145 offset:51200
	ds_read_b128 v[180:183], v145 offset:52224
	ds_read_b128 v[184:187], v145 offset:53248
	ds_read_b128 v[188:191], v145 offset:54272
	ds_read_b128 v[192:195], v145 offset:55296
	ds_read_b128 v[196:199], v145 offset:56320
	global_load_lds_dwordx4 v0, s[98:99]
	s_mov_b32 m0, s75
	s_nop 0
	global_load_lds_dwordx4 v134, s[98:99]
	s_barrier
	s_setprio 1
	s_waitcnt lgkmcnt(7)
	v_mfma_f32_16x16x32_bf16 v[62:65], v[152:155], v[168:171], v[62:65]
	v_mfma_f32_16x16x32_bf16 v[58:61], v[160:163], v[168:171], v[58:61]
	s_waitcnt lgkmcnt(5)
	v_mfma_f32_16x16x32_bf16 v[46:49], v[152:155], v[176:179], v[46:49]
	v_mfma_f32_16x16x32_bf16 v[42:45], v[160:163], v[176:179], v[42:45]
	s_waitcnt lgkmcnt(3)
	v_mfma_f32_16x16x32_bf16 v[30:33], v[152:155], v[184:187], v[30:33]
	v_mfma_f32_16x16x32_bf16 v[26:29], v[160:163], v[184:187], v[26:29]
	s_waitcnt lgkmcnt(1)
	v_mfma_f32_16x16x32_bf16 v[14:17], v[152:155], v[192:195], v[14:17]
	v_mfma_f32_16x16x32_bf16 v[10:13], v[160:163], v[192:195], v[10:13]
	v_mfma_f32_16x16x32_bf16 v[62:65], v[156:159], v[172:175], v[62:65]
	v_mfma_f32_16x16x32_bf16 v[58:61], v[164:167], v[172:175], v[58:61]
	v_mfma_f32_16x16x32_bf16 v[46:49], v[156:159], v[180:183], v[46:49]
	v_mfma_f32_16x16x32_bf16 v[42:45], v[164:167], v[180:183], v[42:45]
	v_mfma_f32_16x16x32_bf16 v[30:33], v[156:159], v[188:191], v[30:33]
	v_mfma_f32_16x16x32_bf16 v[26:29], v[164:167], v[188:191], v[26:29]
	s_waitcnt lgkmcnt(0)
	v_mfma_f32_16x16x32_bf16 v[14:17], v[156:159], v[196:199], v[14:17]
	v_mfma_f32_16x16x32_bf16 v[10:13], v[164:167], v[196:199], v[10:13]
	s_setprio 0
	s_barrier
	s_add_u32 s30, s30, 0x80080
	s_addc_u32 s31, s31, 0
	s_add_i32 s40, s40, s60
	s_mov_b32 m0, s40
	s_nop 0
	global_load_lds_dwordx4 v0, s[30:31]
	s_add_i32 m0, s40, 0x2000
	s_nop 0
	global_load_lds_dwordx4 v134, s[30:31]
	s_waitcnt vmcnt(6)
	s_barrier
	s_setprio 1
	v_mfma_f32_16x16x32_bf16 v[54:57], v[200:203], v[168:171], v[54:57]
	v_mfma_f32_16x16x32_bf16 v[50:53], v[216:219], v[168:171], v[50:53]
	v_mfma_f32_16x16x32_bf16 v[38:41], v[200:203], v[176:179], v[38:41]
	v_mfma_f32_16x16x32_bf16 v[34:37], v[216:219], v[176:179], v[34:37]
	v_mfma_f32_16x16x32_bf16 v[22:25], v[200:203], v[184:187], v[22:25]
	v_mfma_f32_16x16x32_bf16 v[18:21], v[216:219], v[184:187], v[18:21]
	v_mfma_f32_16x16x32_bf16 v[6:9], v[200:203], v[192:195], v[6:9]
	v_mfma_f32_16x16x32_bf16 v[2:5], v[216:219], v[192:195], v[2:5]
	v_mfma_f32_16x16x32_bf16 v[54:57], v[204:207], v[172:175], v[54:57]
	v_mfma_f32_16x16x32_bf16 v[50:53], v[220:223], v[172:175], v[50:53]
	v_mfma_f32_16x16x32_bf16 v[38:41], v[204:207], v[180:183], v[38:41]
	v_mfma_f32_16x16x32_bf16 v[34:37], v[220:223], v[180:183], v[34:37]
	v_mfma_f32_16x16x32_bf16 v[22:25], v[204:207], v[188:191], v[22:25]
	v_mfma_f32_16x16x32_bf16 v[18:21], v[220:223], v[188:191], v[18:21]
	v_mfma_f32_16x16x32_bf16 v[6:9], v[204:207], v[196:199], v[6:9]
	v_mfma_f32_16x16x32_bf16 v[2:5], v[220:223], v[196:199], v[2:5]
	s_setprio 0
	s_add_i32 s45, s45, 2
	s_add_u32 s26, s26, 0x100
	s_addc_u32 s27, s27, 0
	s_cmp_gt_u32 s45, 29
	s_barrier
	s_cbranch_scc0 .LBB0_807
	s_add_u32 s26, s79, 0xffffff00
	s_addc_u32 s27, s80, -1
	s_and_b64 vcc, exec, s[42:43]
	s_cbranch_vccnz .LBB0_796
	v_mov_b32_e32 v2, 0
	s_mov_b32 s14, s8
	s_mov_b32 s50, s77
	s_mov_b64 s[6:7], s[22:23]
	s_mov_b32 s76, s78
	v_mov_b32_e32 v3, v2
	v_mov_b32_e32 v4, v2
	v_mov_b32_e32 v5, v2
	v_mov_b32_e32 v6, v2
	v_mov_b32_e32 v7, v2
	v_mov_b32_e32 v8, v2
	v_mov_b32_e32 v9, v2
	v_mov_b32_e32 v18, v2
	v_mov_b32_e32 v19, v2
	v_mov_b32_e32 v20, v2
	v_mov_b32_e32 v21, v2
	v_mov_b32_e32 v22, v2
	v_mov_b32_e32 v23, v2
	v_mov_b32_e32 v24, v2
	v_mov_b32_e32 v25, v2
	v_mov_b32_e32 v34, v2
	v_mov_b32_e32 v35, v2
	v_mov_b32_e32 v36, v2
	v_mov_b32_e32 v37, v2
	v_mov_b32_e32 v38, v2
	v_mov_b32_e32 v39, v2
	v_mov_b32_e32 v40, v2
	v_mov_b32_e32 v41, v2
	v_mov_b32_e32 v50, v2
	v_mov_b32_e32 v51, v2
	v_mov_b32_e32 v52, v2
	v_mov_b32_e32 v53, v2
	v_mov_b32_e32 v54, v2
	v_mov_b32_e32 v55, v2
	v_mov_b32_e32 v56, v2
	v_mov_b32_e32 v57, v2
	v_mov_b32_e32 v10, v2
	v_mov_b32_e32 v11, v2
	v_mov_b32_e32 v12, v2
	v_mov_b32_e32 v13, v2
	v_mov_b32_e32 v14, v2
	v_mov_b32_e32 v15, v2
	v_mov_b32_e32 v16, v2
	v_mov_b32_e32 v17, v2
	v_mov_b32_e32 v26, v2
	v_mov_b32_e32 v27, v2
	v_mov_b32_e32 v28, v2
	v_mov_b32_e32 v29, v2
	v_mov_b32_e32 v30, v2
	v_mov_b32_e32 v31, v2
	v_mov_b32_e32 v32, v2
	v_mov_b32_e32 v33, v2
	v_mov_b32_e32 v42, v2
	v_mov_b32_e32 v43, v2
	v_mov_b32_e32 v44, v2
	v_mov_b32_e32 v45, v2
	v_mov_b32_e32 v46, v2
	v_mov_b32_e32 v47, v2
	v_mov_b32_e32 v48, v2
	v_mov_b32_e32 v49, v2
	v_mov_b32_e32 v58, v2
	v_mov_b32_e32 v59, v2
	v_mov_b32_e32 v60, v2
	v_mov_b32_e32 v61, v2
	v_mov_b32_e32 v62, v2
	v_mov_b32_e32 v63, v2
	v_mov_b32_e32 v64, v2
	v_mov_b32_e32 v65, v2
	v_mov_b32_e32 v66, v2
	v_mov_b32_e32 v67, v2
	v_mov_b32_e32 v68, v2
	v_mov_b32_e32 v69, v2
	v_mov_b32_e32 v70, v2
	v_mov_b32_e32 v71, v2
	v_mov_b32_e32 v72, v2
	v_mov_b32_e32 v73, v2
	v_mov_b32_e32 v82, v2
	v_mov_b32_e32 v83, v2
	v_mov_b32_e32 v84, v2
	v_mov_b32_e32 v85, v2
	v_mov_b32_e32 v86, v2
	v_mov_b32_e32 v87, v2
	v_mov_b32_e32 v88, v2
	v_mov_b32_e32 v89, v2
	v_mov_b32_e32 v98, v2
	v_mov_b32_e32 v99, v2
	v_mov_b32_e32 v100, v2
	v_mov_b32_e32 v101, v2
	v_mov_b32_e32 v102, v2
	v_mov_b32_e32 v103, v2
	v_mov_b32_e32 v104, v2
	v_mov_b32_e32 v105, v2
	v_mov_b32_e32 v114, v2
	v_mov_b32_e32 v115, v2
	v_mov_b32_e32 v116, v2
	v_mov_b32_e32 v117, v2
	v_mov_b32_e32 v118, v2
	v_mov_b32_e32 v119, v2
	v_mov_b32_e32 v120, v2
	v_mov_b32_e32 v121, v2
	v_mov_b32_e32 v74, v2
	v_mov_b32_e32 v75, v2
	v_mov_b32_e32 v76, v2
	v_mov_b32_e32 v77, v2
	v_mov_b32_e32 v78, v2
	v_mov_b32_e32 v79, v2
	v_mov_b32_e32 v80, v2
	v_mov_b32_e32 v81, v2
	v_mov_b32_e32 v90, v2
	v_mov_b32_e32 v91, v2
	v_mov_b32_e32 v92, v2
	v_mov_b32_e32 v93, v2
	v_mov_b32_e32 v94, v2
	v_mov_b32_e32 v95, v2
	v_mov_b32_e32 v96, v2
	v_mov_b32_e32 v97, v2
	v_mov_b32_e32 v106, v2
	v_mov_b32_e32 v107, v2
	v_mov_b32_e32 v108, v2
	v_mov_b32_e32 v109, v2
	v_mov_b32_e32 v110, v2
	v_mov_b32_e32 v111, v2
	v_mov_b32_e32 v112, v2
	v_mov_b32_e32 v113, v2
	v_mov_b32_e32 v122, v2
	v_mov_b32_e32 v123, v2
	v_mov_b32_e32 v124, v2
	v_mov_b32_e32 v125, v2
	v_mov_b32_e32 v126, v2
	v_mov_b32_e32 v127, v2
	v_mov_b32_e32 v128, v2
	v_mov_b32_e32 v129, v2
	s_andn2_b64 vcc, exec, s[0:1]
	s_cbranch_vccnz .LBB0_797

.LBB0_1084:
	s_add_u32 s30, s6, s22
	s_addc_u32 s31, s7, s23
	s_add_u32 s30, s30, 0x100
	s_addc_u32 s31, s31, 0
	s_add_u32 s79, s42, s22
	s_addc_u32 s80, s43, s23
	s_add_i32 s81, 0, 0x10000
	v_add_u32_e32 v149, s81, v146
	ds_read_b128 v[152:155], v149
	ds_read_b128 v[156:159], v149 offset:1024
	ds_read_b128 v[160:163], v149 offset:2048
	ds_read_b128 v[164:167], v149 offset:3072
	s_cmpk_eq_i32 s22, 0x2a00
	s_cselect_b32 s41, s13, s31
	s_cselect_b32 s40, s12, s30
	s_cselect_b32 s31, s9, s80
	s_cselect_b32 s30, s8, s79
	v_lshl_add_u64 v[200:201], v[142:143], 0, s[22:23]
	s_add_i32 m0, s53, 0xc000
	ds_read_b128 v[168:171], v147
	ds_read_b128 v[172:175], v147 offset:1024
	ds_read_b128 v[176:179], v147 offset:2048
	ds_read_b128 v[180:183], v147 offset:3072
	ds_read_b128 v[184:187], v147 offset:4096
	ds_read_b128 v[188:191], v147 offset:5120
	ds_read_b128 v[192:195], v147 offset:6144
	ds_read_b128 v[196:199], v147 offset:7168
	global_load_lds_dwordx4 v[200:201], off
	v_lshl_add_u64 v[200:201], v[144:145], 0, s[22:23]
	s_add_i32 m0, s53, 0xe000
	s_nop 0
	global_load_lds_dwordx4 v[200:201], off
	s_waitcnt lgkmcnt(8)
	s_barrier
	s_setprio 1
	s_waitcnt lgkmcnt(7)
	v_mfma_f32_16x16x32_bf16 v[126:129], v[152:155], v[168:171], v[126:129]
	v_mfma_f32_16x16x32_bf16 v[122:125], v[160:163], v[168:171], v[122:125]
	s_waitcnt lgkmcnt(5)
	v_mfma_f32_16x16x32_bf16 v[110:113], v[152:155], v[176:179], v[110:113]
	v_mfma_f32_16x16x32_bf16 v[106:109], v[160:163], v[176:179], v[106:109]
	s_waitcnt lgkmcnt(3)
	v_mfma_f32_16x16x32_bf16 v[94:97], v[152:155], v[184:187], v[94:97]
	v_mfma_f32_16x16x32_bf16 v[90:93], v[160:163], v[184:187], v[90:93]
	s_waitcnt lgkmcnt(1)
	v_mfma_f32_16x16x32_bf16 v[78:81], v[152:155], v[192:195], v[78:81]
	v_mfma_f32_16x16x32_bf16 v[74:77], v[160:163], v[192:195], v[74:77]
	v_mfma_f32_16x16x32_bf16 v[126:129], v[156:159], v[172:175], v[126:129]
	v_mfma_f32_16x16x32_bf16 v[122:125], v[164:167], v[172:175], v[122:125]
	v_mfma_f32_16x16x32_bf16 v[110:113], v[156:159], v[180:183], v[110:113]
	v_mfma_f32_16x16x32_bf16 v[106:109], v[164:167], v[180:183], v[106:109]
	v_mfma_f32_16x16x32_bf16 v[94:97], v[156:159], v[188:191], v[94:97]
	v_mfma_f32_16x16x32_bf16 v[90:93], v[164:167], v[188:191], v[90:93]
	s_waitcnt lgkmcnt(0)
	v_mfma_f32_16x16x32_bf16 v[78:81], v[156:159], v[196:199], v[78:81]
	v_mfma_f32_16x16x32_bf16 v[74:77], v[164:167], v[196:199], v[74:77]
	s_setprio 0
	s_barrier
	s_add_i32 s79, 0, 0x14000
	s_add_i32 s80, s81, s52
	v_add_u32_e32 v149, s79, v146
	s_mov_b32 m0, s80
	ds_read_b128 v[200:203], v149
	ds_read_b128 v[204:207], v149 offset:1024
	ds_read_b128 v[216:219], v149 offset:2048
	ds_read_b128 v[220:223], v149 offset:3072
	global_load_lds_dwordx4 v0, s[30:31]
	s_add_i32 m0, s80, 0x2000
	s_nop 0
	global_load_lds_dwordx4 v136, s[30:31]
	s_barrier
	s_setprio 1
	s_waitcnt lgkmcnt(3)
	v_mfma_f32_16x16x32_bf16 v[118:121], v[200:203], v[168:171], v[118:121]
	s_waitcnt lgkmcnt(1)
	v_mfma_f32_16x16x32_bf16 v[114:117], v[216:219], v[168:171], v[114:117]
	v_mfma_f32_16x16x32_bf16 v[102:105], v[200:203], v[176:179], v[102:105]
	v_mfma_f32_16x16x32_bf16 v[98:101], v[216:219], v[176:179], v[98:101]
	v_mfma_f32_16x16x32_bf16 v[86:89], v[200:203], v[184:187], v[86:89]
	v_mfma_f32_16x16x32_bf16 v[82:85], v[216:219], v[184:187], v[82:85]
	v_mfma_f32_16x16x32_bf16 v[70:73], v[200:203], v[192:195], v[70:73]
	v_mfma_f32_16x16x32_bf16 v[66:69], v[216:219], v[192:195], v[66:69]
	v_mfma_f32_16x16x32_bf16 v[118:121], v[204:207], v[172:175], v[118:121]
	s_waitcnt lgkmcnt(0)
	v_mfma_f32_16x16x32_bf16 v[114:117], v[220:223], v[172:175], v[114:117]
	v_mfma_f32_16x16x32_bf16 v[102:105], v[204:207], v[180:183], v[102:105]
	v_mfma_f32_16x16x32_bf16 v[98:101], v[220:223], v[180:183], v[98:101]
	v_mfma_f32_16x16x32_bf16 v[86:89], v[204:207], v[188:191], v[86:89]
	v_mfma_f32_16x16x32_bf16 v[82:85], v[220:223], v[188:191], v[82:85]
	v_mfma_f32_16x16x32_bf16 v[70:73], v[204:207], v[196:199], v[70:73]
	v_mfma_f32_16x16x32_bf16 v[66:69], v[220:223], v[196:199], v[66:69]
	s_setprio 0
	s_mov_b32 m0, s53
	s_add_u32 s98, s40, 0x80
	s_addc_u32 s99, s41, 0
	s_barrier
	ds_read_b128 v[168:171], v147 offset:16384
	ds_read_b128 v[172:175], v147 offset:17408
	ds_read_b128 v[176:179], v147 offset:18432
	ds_read_b128 v[180:183], v147 offset:19456
	ds_read_b128 v[184:187], v147 offset:20480
	ds_read_b128 v[188:191], v147 offset:21504
	ds_read_b128 v[192:195], v147 offset:22528
	ds_read_b128 v[196:199], v147 offset:23552
	global_load_lds_dwordx4 v0, s[40:41]
	s_mov_b32 m0, s60
	s_nop 0
	global_load_lds_dwordx4 v136, s[40:41]
	s_barrier
	s_setprio 1
	s_waitcnt lgkmcnt(7)
	v_mfma_f32_16x16x32_bf16 v[62:65], v[152:155], v[168:171], v[62:65]
	v_mfma_f32_16x16x32_bf16 v[58:61], v[160:163], v[168:171], v[58:61]
	s_waitcnt lgkmcnt(5)
	v_mfma_f32_16x16x32_bf16 v[46:49], v[152:155], v[176:179], v[46:49]
	v_mfma_f32_16x16x32_bf16 v[42:45], v[160:163], v[176:179], v[42:45]
	s_waitcnt lgkmcnt(3)
	v_mfma_f32_16x16x32_bf16 v[30:33], v[152:155], v[184:187], v[30:33]
	v_mfma_f32_16x16x32_bf16 v[26:29], v[160:163], v[184:187], v[26:29]
	s_waitcnt lgkmcnt(1)
	v_mfma_f32_16x16x32_bf16 v[14:17], v[152:155], v[192:195], v[14:17]
	v_mfma_f32_16x16x32_bf16 v[10:13], v[160:163], v[192:195], v[10:13]
	v_mfma_f32_16x16x32_bf16 v[62:65], v[156:159], v[172:175], v[62:65]
	v_mfma_f32_16x16x32_bf16 v[58:61], v[164:167], v[172:175], v[58:61]
	v_mfma_f32_16x16x32_bf16 v[46:49], v[156:159], v[180:183], v[46:49]
	v_mfma_f32_16x16x32_bf16 v[42:45], v[164:167], v[180:183], v[42:45]
	v_mfma_f32_16x16x32_bf16 v[30:33], v[156:159], v[188:191], v[30:33]
	v_mfma_f32_16x16x32_bf16 v[26:29], v[164:167], v[188:191], v[26:29]
	s_waitcnt lgkmcnt(0)
	v_mfma_f32_16x16x32_bf16 v[14:17], v[156:159], v[196:199], v[14:17]
	v_mfma_f32_16x16x32_bf16 v[10:13], v[164:167], v[196:199], v[10:13]
	s_setprio 0
	s_barrier
	s_add_u32 s80, s30, 0x158000
	s_addc_u32 s81, s31, 0
	s_add_i32 s79, s79, s52
	s_mov_b32 m0, s79
	s_nop 0
	global_load_lds_dwordx4 v0, s[80:81]
	s_add_i32 m0, s79, 0x2000
	s_nop 0
	global_load_lds_dwordx4 v136, s[80:81]
	s_waitcnt vmcnt(6)
	s_barrier
	s_setprio 1
	v_mfma_f32_16x16x32_bf16 v[54:57], v[200:203], v[168:171], v[54:57]
	v_mfma_f32_16x16x32_bf16 v[50:53], v[216:219], v[168:171], v[50:53]
	v_mfma_f32_16x16x32_bf16 v[38:41], v[200:203], v[176:179], v[38:41]
	v_mfma_f32_16x16x32_bf16 v[34:37], v[216:219], v[176:179], v[34:37]
	v_mfma_f32_16x16x32_bf16 v[22:25], v[200:203], v[184:187], v[22:25]
	v_mfma_f32_16x16x32_bf16 v[18:21], v[216:219], v[184:187], v[18:21]
	v_mfma_f32_16x16x32_bf16 v[6:9], v[200:203], v[192:195], v[6:9]
	v_mfma_f32_16x16x32_bf16 v[2:5], v[216:219], v[192:195], v[2:5]
	v_mfma_f32_16x16x32_bf16 v[54:57], v[204:207], v[172:175], v[54:57]
	v_mfma_f32_16x16x32_bf16 v[50:53], v[220:223], v[172:175], v[50:53]
	v_mfma_f32_16x16x32_bf16 v[38:41], v[204:207], v[180:183], v[38:41]
	v_mfma_f32_16x16x32_bf16 v[34:37], v[220:223], v[180:183], v[34:37]
	v_mfma_f32_16x16x32_bf16 v[22:25], v[204:207], v[188:191], v[22:25]
	v_mfma_f32_16x16x32_bf16 v[18:21], v[220:223], v[188:191], v[18:21]
	v_mfma_f32_16x16x32_bf16 v[6:9], v[204:207], v[196:199], v[6:9]
	v_mfma_f32_16x16x32_bf16 v[2:5], v[220:223], v[196:199], v[2:5]
	s_setprio 0
	s_add_i32 s79, 0, 0x18000
	v_add_u32_e32 v149, s79, v146
	s_barrier
	ds_read_b128 v[152:155], v149
	ds_read_b128 v[156:159], v149 offset:1024
	ds_read_b128 v[160:163], v149 offset:2048
	ds_read_b128 v[164:167], v149 offset:3072
	s_add_u32 s40, s40, 0x158000
	s_addc_u32 s41, s41, 0
	s_mov_b32 m0, s65
	ds_read_b128 v[168:171], v147 offset:32768
	ds_read_b128 v[172:175], v147 offset:33792
	ds_read_b128 v[176:179], v147 offset:34816
	ds_read_b128 v[180:183], v147 offset:35840
	ds_read_b128 v[184:187], v147 offset:36864
	ds_read_b128 v[188:191], v147 offset:37888
	ds_read_b128 v[192:195], v147 offset:38912
	ds_read_b128 v[196:199], v147 offset:39936
	global_load_lds_dwordx4 v0, s[40:41]
	s_mov_b32 m0, s66
	s_nop 0
	global_load_lds_dwordx4 v136, s[40:41]
	s_waitcnt lgkmcnt(8)
	s_barrier
	s_setprio 1
	s_waitcnt lgkmcnt(7)
	v_mfma_f32_16x16x32_bf16 v[126:129], v[152:155], v[168:171], v[126:129]
	v_mfma_f32_16x16x32_bf16 v[122:125], v[160:163], v[168:171], v[122:125]
	s_waitcnt lgkmcnt(5)
	v_mfma_f32_16x16x32_bf16 v[110:113], v[152:155], v[176:179], v[110:113]
	v_mfma_f32_16x16x32_bf16 v[106:109], v[160:163], v[176:179], v[106:109]
	s_waitcnt lgkmcnt(3)
	v_mfma_f32_16x16x32_bf16 v[94:97], v[152:155], v[184:187], v[94:97]
	v_mfma_f32_16x16x32_bf16 v[90:93], v[160:163], v[184:187], v[90:93]
	s_waitcnt lgkmcnt(1)
	v_mfma_f32_16x16x32_bf16 v[78:81], v[152:155], v[192:195], v[78:81]
	v_mfma_f32_16x16x32_bf16 v[74:77], v[160:163], v[192:195], v[74:77]
	v_mfma_f32_16x16x32_bf16 v[126:129], v[156:159], v[172:175], v[126:129]
	v_mfma_f32_16x16x32_bf16 v[122:125], v[164:167], v[172:175], v[122:125]
	v_mfma_f32_16x16x32_bf16 v[110:113], v[156:159], v[180:183], v[110:113]
	v_mfma_f32_16x16x32_bf16 v[106:109], v[164:167], v[180:183], v[106:109]
	v_mfma_f32_16x16x32_bf16 v[94:97], v[156:159], v[188:191], v[94:97]
	v_mfma_f32_16x16x32_bf16 v[90:93], v[164:167], v[188:191], v[90:93]
	s_waitcnt lgkmcnt(0)
	v_mfma_f32_16x16x32_bf16 v[78:81], v[156:159], v[196:199], v[78:81]
	v_mfma_f32_16x16x32_bf16 v[74:77], v[164:167], v[196:199], v[74:77]
	s_setprio 0
	s_barrier
	s_add_i32 s40, 0, 0x1c000
	s_add_i32 s41, s79, s52
	v_add_u32_e32 v149, s40, v146
	s_add_u32 s100, s30, 0x80
	s_addc_u32 s101, s31, 0
	s_mov_b32 m0, s41
	ds_read_b128 v[200:203], v149
	ds_read_b128 v[204:207], v149 offset:1024
	ds_read_b128 v[216:219], v149 offset:2048
	ds_read_b128 v[220:223], v149 offset:3072
	global_load_lds_dwordx4 v0, s[100:101]
	s_add_i32 m0, s41, 0x2000
	s_nop 0
	global_load_lds_dwordx4 v136, s[100:101]
	s_barrier
	s_setprio 1
	s_waitcnt lgkmcnt(3)
	v_mfma_f32_16x16x32_bf16 v[118:121], v[200:203], v[168:171], v[118:121]
	s_waitcnt lgkmcnt(1)
	v_mfma_f32_16x16x32_bf16 v[114:117], v[216:219], v[168:171], v[114:117]
	v_mfma_f32_16x16x32_bf16 v[102:105], v[200:203], v[176:179], v[102:105]
	v_mfma_f32_16x16x32_bf16 v[98:101], v[216:219], v[176:179], v[98:101]
	v_mfma_f32_16x16x32_bf16 v[86:89], v[200:203], v[184:187], v[86:89]
	v_mfma_f32_16x16x32_bf16 v[82:85], v[216:219], v[184:187], v[82:85]
	v_mfma_f32_16x16x32_bf16 v[70:73], v[200:203], v[192:195], v[70:73]
	v_mfma_f32_16x16x32_bf16 v[66:69], v[216:219], v[192:195], v[66:69]
	v_mfma_f32_16x16x32_bf16 v[118:121], v[204:207], v[172:175], v[118:121]
	s_waitcnt lgkmcnt(0)
	v_mfma_f32_16x16x32_bf16 v[114:117], v[220:223], v[172:175], v[114:117]
	v_mfma_f32_16x16x32_bf16 v[102:105], v[204:207], v[180:183], v[102:105]
	v_mfma_f32_16x16x32_bf16 v[98:101], v[220:223], v[180:183], v[98:101]
	v_mfma_f32_16x16x32_bf16 v[86:89], v[204:207], v[188:191], v[86:89]
	v_mfma_f32_16x16x32_bf16 v[82:85], v[220:223], v[188:191], v[82:85]
	v_mfma_f32_16x16x32_bf16 v[70:73], v[204:207], v[196:199], v[70:73]
	v_mfma_f32_16x16x32_bf16 v[66:69], v[220:223], v[196:199], v[66:69]
	s_setprio 0
	s_mov_b32 m0, s67
	s_barrier
	ds_read_b128 v[168:171], v147 offset:49152
	ds_read_b128 v[172:175], v147 offset:50176
	ds_read_b128 v[176:179], v147 offset:51200
	ds_read_b128 v[180:183], v147 offset:52224
	ds_read_b128 v[184:187], v147 offset:53248
	ds_read_b128 v[188:191], v147 offset:54272
	ds_read_b128 v[192:195], v147 offset:55296
	ds_read_b128 v[196:199], v147 offset:56320
	global_load_lds_dwordx4 v0, s[98:99]
	s_mov_b32 m0, s68
	s_nop 0
	global_load_lds_dwordx4 v136, s[98:99]
	s_barrier
	s_setprio 1
	s_waitcnt lgkmcnt(7)
	v_mfma_f32_16x16x32_bf16 v[62:65], v[152:155], v[168:171], v[62:65]
	v_mfma_f32_16x16x32_bf16 v[58:61], v[160:163], v[168:171], v[58:61]
	s_waitcnt lgkmcnt(5)
	v_mfma_f32_16x16x32_bf16 v[46:49], v[152:155], v[176:179], v[46:49]
	v_mfma_f32_16x16x32_bf16 v[42:45], v[160:163], v[176:179], v[42:45]
	s_waitcnt lgkmcnt(3)
	v_mfma_f32_16x16x32_bf16 v[30:33], v[152:155], v[184:187], v[30:33]
	v_mfma_f32_16x16x32_bf16 v[26:29], v[160:163], v[184:187], v[26:29]
	s_waitcnt lgkmcnt(1)
	v_mfma_f32_16x16x32_bf16 v[14:17], v[152:155], v[192:195], v[14:17]
	v_mfma_f32_16x16x32_bf16 v[10:13], v[160:163], v[192:195], v[10:13]
	v_mfma_f32_16x16x32_bf16 v[62:65], v[156:159], v[172:175], v[62:65]
	v_mfma_f32_16x16x32_bf16 v[58:61], v[164:167], v[172:175], v[58:61]
	v_mfma_f32_16x16x32_bf16 v[46:49], v[156:159], v[180:183], v[46:49]
	v_mfma_f32_16x16x32_bf16 v[42:45], v[164:167], v[180:183], v[42:45]
	v_mfma_f32_16x16x32_bf16 v[30:33], v[156:159], v[188:191], v[30:33]
	v_mfma_f32_16x16x32_bf16 v[26:29], v[164:167], v[188:191], v[26:29]
	s_waitcnt lgkmcnt(0)
	v_mfma_f32_16x16x32_bf16 v[14:17], v[156:159], v[196:199], v[14:17]
	v_mfma_f32_16x16x32_bf16 v[10:13], v[164:167], v[196:199], v[10:13]
	s_setprio 0
	s_barrier
	s_add_u32 s30, s30, 0x158080
	s_addc_u32 s31, s31, 0
	s_add_i32 s40, s40, s52
	s_mov_b32 m0, s40
	s_nop 0
	global_load_lds_dwordx4 v0, s[30:31]
	s_add_i32 m0, s40, 0x2000
	s_nop 0
	global_load_lds_dwordx4 v136, s[30:31]
	s_waitcnt vmcnt(6)
	s_barrier
	s_setprio 1
	v_mfma_f32_16x16x32_bf16 v[54:57], v[200:203], v[168:171], v[54:57]
	v_mfma_f32_16x16x32_bf16 v[50:53], v[216:219], v[168:171], v[50:53]
	v_mfma_f32_16x16x32_bf16 v[38:41], v[200:203], v[176:179], v[38:41]
	v_mfma_f32_16x16x32_bf16 v[34:37], v[216:219], v[176:179], v[34:37]
	v_mfma_f32_16x16x32_bf16 v[22:25], v[200:203], v[184:187], v[22:25]
	v_mfma_f32_16x16x32_bf16 v[18:21], v[216:219], v[184:187], v[18:21]
	v_mfma_f32_16x16x32_bf16 v[6:9], v[200:203], v[192:195], v[6:9]
	v_mfma_f32_16x16x32_bf16 v[2:5], v[216:219], v[192:195], v[2:5]
	v_mfma_f32_16x16x32_bf16 v[54:57], v[204:207], v[172:175], v[54:57]
	v_mfma_f32_16x16x32_bf16 v[50:53], v[220:223], v[172:175], v[50:53]
	v_mfma_f32_16x16x32_bf16 v[38:41], v[204:207], v[180:183], v[38:41]
	v_mfma_f32_16x16x32_bf16 v[34:37], v[220:223], v[180:183], v[34:37]
	v_mfma_f32_16x16x32_bf16 v[22:25], v[204:207], v[188:191], v[22:25]
	v_mfma_f32_16x16x32_bf16 v[18:21], v[220:223], v[188:191], v[18:21]
	v_mfma_f32_16x16x32_bf16 v[6:9], v[204:207], v[196:199], v[6:9]
	v_mfma_f32_16x16x32_bf16 v[2:5], v[220:223], v[196:199], v[2:5]
	s_setprio 0
	s_add_i32 s78, s78, 2
	s_add_u32 s22, s22, 0x100
	s_addc_u32 s23, s23, 0
	s_cmpk_gt_u32 s78, 0x53
	s_barrier
	s_cbranch_scc0 .LBB0_1084
	s_add_u32 s22, s42, 0xffffff00
	s_addc_u32 s23, s43, -1
	s_and_b64 vcc, exec, s[38:39]
	s_cbranch_vccnz .LBB0_1071
	v_mov_b32_e32 v2, 0
	s_mov_b32 s14, s75
	s_mov_b32 s50, s76
	s_mov_b64 s[6:7], s[12:13]
	s_mov_b32 s69, s77
	v_mov_b32_e32 v3, v2
	v_mov_b32_e32 v4, v2
	v_mov_b32_e32 v5, v2
	v_mov_b32_e32 v6, v2
	v_mov_b32_e32 v7, v2
	v_mov_b32_e32 v8, v2
	v_mov_b32_e32 v9, v2
	v_mov_b32_e32 v18, v2
	v_mov_b32_e32 v19, v2
	v_mov_b32_e32 v20, v2
	v_mov_b32_e32 v21, v2
	v_mov_b32_e32 v22, v2
	v_mov_b32_e32 v23, v2
	v_mov_b32_e32 v24, v2
	v_mov_b32_e32 v25, v2
	v_mov_b32_e32 v34, v2
	v_mov_b32_e32 v35, v2
	v_mov_b32_e32 v36, v2
	v_mov_b32_e32 v37, v2
	v_mov_b32_e32 v38, v2
	v_mov_b32_e32 v39, v2
	v_mov_b32_e32 v40, v2
	v_mov_b32_e32 v41, v2
	v_mov_b32_e32 v50, v2
	v_mov_b32_e32 v51, v2
	v_mov_b32_e32 v52, v2
	v_mov_b32_e32 v53, v2
	v_mov_b32_e32 v54, v2
	v_mov_b32_e32 v55, v2
	v_mov_b32_e32 v56, v2
	v_mov_b32_e32 v57, v2
	v_mov_b32_e32 v10, v2
	v_mov_b32_e32 v11, v2
	v_mov_b32_e32 v12, v2
	v_mov_b32_e32 v13, v2
	v_mov_b32_e32 v14, v2
	v_mov_b32_e32 v15, v2
	v_mov_b32_e32 v16, v2
	v_mov_b32_e32 v17, v2
	v_mov_b32_e32 v26, v2
	v_mov_b32_e32 v27, v2
	v_mov_b32_e32 v28, v2
	v_mov_b32_e32 v29, v2
	v_mov_b32_e32 v30, v2
	v_mov_b32_e32 v31, v2
	v_mov_b32_e32 v32, v2
	v_mov_b32_e32 v33, v2
	v_mov_b32_e32 v42, v2
	v_mov_b32_e32 v43, v2
	v_mov_b32_e32 v44, v2
	v_mov_b32_e32 v45, v2
	v_mov_b32_e32 v46, v2
	v_mov_b32_e32 v47, v2
	v_mov_b32_e32 v48, v2
	v_mov_b32_e32 v49, v2
	v_mov_b32_e32 v58, v2
	v_mov_b32_e32 v59, v2
	v_mov_b32_e32 v60, v2
	v_mov_b32_e32 v61, v2
	v_mov_b32_e32 v62, v2
	v_mov_b32_e32 v63, v2
	v_mov_b32_e32 v64, v2
	v_mov_b32_e32 v65, v2
	v_mov_b32_e32 v66, v2
	v_mov_b32_e32 v67, v2
	v_mov_b32_e32 v68, v2
	v_mov_b32_e32 v69, v2
	v_mov_b32_e32 v70, v2
	v_mov_b32_e32 v71, v2
	v_mov_b32_e32 v72, v2
	v_mov_b32_e32 v73, v2
	v_mov_b32_e32 v82, v2
	v_mov_b32_e32 v83, v2
	v_mov_b32_e32 v84, v2
	v_mov_b32_e32 v85, v2
	v_mov_b32_e32 v86, v2
	v_mov_b32_e32 v87, v2
	v_mov_b32_e32 v88, v2
	v_mov_b32_e32 v89, v2
	v_mov_b32_e32 v98, v2
	v_mov_b32_e32 v99, v2
	v_mov_b32_e32 v100, v2
	v_mov_b32_e32 v101, v2
	v_mov_b32_e32 v102, v2
	v_mov_b32_e32 v103, v2
	v_mov_b32_e32 v104, v2
	v_mov_b32_e32 v105, v2
	v_mov_b32_e32 v114, v2
	v_mov_b32_e32 v115, v2
	v_mov_b32_e32 v116, v2
	v_mov_b32_e32 v117, v2
	v_mov_b32_e32 v118, v2
	v_mov_b32_e32 v119, v2
	v_mov_b32_e32 v120, v2
	v_mov_b32_e32 v121, v2
	v_mov_b32_e32 v74, v2
	v_mov_b32_e32 v75, v2
	v_mov_b32_e32 v76, v2
	v_mov_b32_e32 v77, v2
	v_mov_b32_e32 v78, v2
	v_mov_b32_e32 v79, v2
	v_mov_b32_e32 v80, v2
	v_mov_b32_e32 v81, v2
	v_mov_b32_e32 v90, v2
	v_mov_b32_e32 v91, v2
	v_mov_b32_e32 v92, v2
	v_mov_b32_e32 v93, v2
	v_mov_b32_e32 v94, v2
	v_mov_b32_e32 v95, v2
	v_mov_b32_e32 v96, v2
	v_mov_b32_e32 v97, v2
	v_mov_b32_e32 v106, v2
	v_mov_b32_e32 v107, v2
	v_mov_b32_e32 v108, v2
	v_mov_b32_e32 v109, v2
	v_mov_b32_e32 v110, v2
	v_mov_b32_e32 v111, v2
	v_mov_b32_e32 v112, v2
	v_mov_b32_e32 v113, v2
	v_mov_b32_e32 v122, v2
	v_mov_b32_e32 v123, v2
	v_mov_b32_e32 v124, v2
	v_mov_b32_e32 v125, v2
	v_mov_b32_e32 v126, v2
	v_mov_b32_e32 v127, v2
	v_mov_b32_e32 v128, v2
	v_mov_b32_e32 v129, v2
	s_andn2_b64 vcc, exec, s[0:1]
	s_cbranch_vccnz .LBB0_1072
